# RWKV chain: y row-sum reduction deferred to a per-chunk DPP butterfly reduce-scatter
# speedup vs baseline: 1.0850x; 1.0045x over previous
; DEVI void rw_chain_task(const Params& p, int l, int seq, int head, int quarter, char* smem) {
;     ...
;   int lstride0, ldstA0, ldB;
;   {
;     const int step = tid >> 6;
;     int q = tid & 63;
;     if (q >= 56) q -= 8;
;     const size_t g = gbase + step;
;     if (q < 32) {
;       const int arr = q >> 3, qq = q & 7;
;       int off;
;       if (arr == 0) { lsrc0 = (gptr_t)(zC + g * LZC + head * 64 + qq * 8); lstride0 = LZC * 2; off = 24; }
;       else if (arr == 1) { lsrc0 = (gptr_t)(zC + g * LZC + 768 + head * 64 + qq * 8); lstride0 = LZC * 2; off = 16; }
;       else if (arr == 2) { lsrc0 = (gptr_t)(KK + g * 768 + head * 64 + qq * 8); lstride0 = 768 * 2; off = 0; }
;       else { lsrc0 = (gptr_t)(BB + g * 768 + head * 64 + qq * 8); lstride0 = 768 * 2; off = 8; }
;       ldstA0 = step * 896 + (2 * qq) * 48 + off;
;       ldB = 48;
;     } else if (q < 48) {
;       lsrc0 = (gptr_t)(WW + g * 768 + head * 64 + (q - 32) * 4); lstride0 = 768 * 4;
;       ldstA0 = step * 896 + (q - 32) * 48 + 32;
;       ldB = 8;
;     } else {
;       lsrc0 = (gptr_t)(zC + g * LZC + 1536 + head * 64 + (q - 48) * 8); lstride0 = LZC * 2;
;       ldstA0 = step * 896 + 768 + (q - 48) * 16;
;       ldB = 8;
;     }
;   }
;   u32x4 R0[4], R1[4], R2[4], R3[4];
;     ...
;   RW_LOAD(R0, 0);
;   RW_LOAD(R1, 1);
;   RW_LOAD(R2, 2);
;   RW_LOAD(R3, 3);
;   RW_STORE(R0, B0);
;   RW_LOAD(R0, 4);
.LBB0_975:
	s_waitcnt vmcnt(0) lgkmcnt(0)
	s_barrier
	v_readlane_b32 s38, v251, 1
	v_readlane_b32 s39, v251, 2
	v_readlane_b32 s41, v253, 37
	v_readlane_b32 s42, v253, 4
	v_readlane_b32 s43, v252, 61
	v_and_b32_e32 v3, 15, v1
	v_lshrrev_b32_e32 v5, 6, v1
	v_bfe_u32 v6, v1, 4, 2
	v_lshl_add_u32 v154, v5, 2, v6
	s_lshl_b32 s45, s41, 14
	s_lshl_b32 s46, s42, 7
	s_lshl_b32 s47, s41, 26
	v_add_u32_e32 v154, s43, v154
	v_and_b32_e32 v7, 31, v1
	v_lshrrev_b32_e32 v8, 3, v7
	v_and_b32_e32 v9, 7, v1
	v_lshrrev_b32_e32 v10, 5, v1
	v_lshrrev_b32_e32 v11, 1, v8
	v_and_b32_e32 v12, 1, v8
	v_cmp_ne_u32_e64 s[4:5], 0, v12
	v_cmp_ne_u32_e64 s[6:7], 0, v11
	v_mov_b32_e32 v14, 0x1cfd0000
	v_mov_b32_e32 v15, 0x1cfd0600
	v_mov_b32_e32 v16, 0x318b3000
	v_mov_b32_e32 v17, 0x34913000
	v_cndmask_b32_e64 v14, v14, v15, s[4:5]
	v_cndmask_b32_e64 v16, v16, v17, s[4:5]
	v_cndmask_b32_e64 v14, v14, v16, s[6:7]
	v_mov_b32_e32 v15, 0x1400
	v_mov_b32_e32 v17, 0x600
	v_cndmask_b32_e64 v13, v15, v17, s[6:7]
	v_xor_b32_e32 v18, 3, v8
	v_xor_b32_e32 v19, 2, v8
	v_cndmask_b32_e64 v18, v18, v19, s[6:7]
	v_lshl_add_u32 v14, v9, 4, v14
	v_add_u32_e32 v14, s46, v14
	v_add_u32_e32 v20, s45, v10
	v_mad_u32_u24 v14, v20, v13, v14
	v_mov_b32_e32 v15, 0
	v_lshl_add_u64 v[144:145], v[14:15], 0, s[38:39]
	v_lshlrev_b32_e32 v16, 3, v13
	v_mov_b32_e32 v17, 0
	v_lshl_add_u64 v[146:147], v[144:145], 0, v[16:17]
	v_lshlrev_b32_e32 v152, 4, v13
	v_mov_b32_e32 v153, 0
	v_mul_u32_u24_e32 v164, 0x580, v10
	v_mul_u32_u24_e32 v21, 0xa0, v9
	v_add_u32_e32 v164, v164, v21
	v_lshl_add_u32 v164, v18, 4, v164
	v_lshrrev_b32_e32 v22, 4, v1
	v_add_u32_e32 v20, s45, v22
	v_mov_b32_e32 v14, 0x37973000
	v_lshl_add_u32 v14, v3, 4, v14
	v_lshl_add_u32 v14, s42, 8, v14
	v_mov_b32_e32 v13, 0xc00
	v_mad_u32_u24 v14, v20, v13, v14
	v_lshl_add_u64 v[148:149], v[14:15], 0, s[38:39]
	v_mul_u32_u24_e32 v167, 0x580, v22
	v_mul_u32_u24_e32 v21, 0x50, v3
	v_add3_u32 v167, v167, v21, 64
	v_bfe_u32 v23, v1, 1, 3
	v_mov_b32_e32 v14, 0x1cfd0c00
	v_lshl_add_u32 v14, v23, 4, v14
	v_add_u32_e32 v14, s46, v14
	v_mov_b32_e32 v13, 0x1400
	v_mad_u32_u24 v14, v20, v13, v14
	v_lshl_add_u64 v[150:151], v[14:15], 0, s[38:39]
	v_mul_u32_u24_e32 v168, 0x580, v22
	v_lshl_add_u32 v168, v23, 4, v168
	v_add_u32_e32 v168, 0x500, v168
	v_mov_b32_e32 v62, 0xc000
	v_mov_b32_e32 v63, 0
	v_mov_b32_e32 v64, 0x14000
	v_mov_b32_e32 v65, 0
	v_mul_u32_u24_e32 v162, 0x50, v3
	v_lshlrev_b32_e32 v163, 1, v154
	v_add_u32_e32 v163, 0x500, v163
	v_lshlrev_b32_e32 v14, 12, v3
	v_lshl_add_u32 v14, v154, 1, v14
	v_add_u32_e32 v14, s47, v14
	v_add_u32_e32 v14, s46, v14
	v_add_u32_e32 v14, 0x2480a00, v14
	v_lshl_add_u64 v[160:161], v[14:15], 0, s[38:39]
	global_load_dwordx4 v[72:75], v[144:145], off
	global_load_dwordx4 v[76:79], v[146:147], off
	global_load_dwordx4 v[80:83], v[148:149], off
	global_load_dwordx4 v[84:87], v[150:151], off
	v_lshl_add_u64 v[144:145], v[144:145], 0, v[152:153]
	v_lshl_add_u64 v[146:147], v[146:147], 0, v[152:153]
	v_lshl_add_u64 v[148:149], v[148:149], 0, v[62:63]
	v_lshl_add_u64 v[150:151], v[150:151], 0, v[64:65]
	global_load_dwordx4 v[88:91], v[144:145], off
	global_load_dwordx4 v[92:95], v[146:147], off
	global_load_dwordx4 v[96:99], v[148:149], off
	global_load_dwordx4 v[100:103], v[150:151], off
	v_lshl_add_u64 v[144:145], v[144:145], 0, v[152:153]
	v_lshl_add_u64 v[146:147], v[146:147], 0, v[152:153]
	v_lshl_add_u64 v[148:149], v[148:149], 0, v[62:63]
	v_lshl_add_u64 v[150:151], v[150:151], 0, v[64:65]
	global_load_dwordx4 v[104:107], v[144:145], off
	global_load_dwordx4 v[108:111], v[146:147], off
	global_load_dwordx4 v[112:115], v[148:149], off
	global_load_dwordx4 v[116:119], v[150:151], off
	v_lshl_add_u64 v[144:145], v[144:145], 0, v[152:153]
	v_lshl_add_u64 v[146:147], v[146:147], 0, v[152:153]
	v_lshl_add_u64 v[148:149], v[148:149], 0, v[62:63]
	v_lshl_add_u64 v[150:151], v[150:151], 0, v[64:65]
	global_load_dwordx4 v[120:123], v[144:145], off
	global_load_dwordx4 v[124:127], v[146:147], off
	global_load_dwordx4 v[128:131], v[148:149], off
	global_load_dwordx4 v[132:135], v[150:151], off
	v_lshl_add_u64 v[144:145], v[144:145], 0, v[152:153]
	v_lshl_add_u64 v[146:147], v[146:147], 0, v[152:153]
	v_lshl_add_u64 v[148:149], v[148:149], 0, v[62:63]
	v_lshl_add_u64 v[150:151], v[150:151], 0, v[64:65]
	v_and_b32_e32 v14, 2, v3
	v_and_b32_e32 v15, 1, v3
	v_cmp_ne_u32_e64 s[4:5], 0, v14
	v_cmp_ne_u32_e64 s[6:7], 0, v15
	v_mov_b32_e32 v68, 0
	v_mov_b32_e32 v69, 0
	v_mov_b32_e32 v70, 0
	v_mov_b32_e32 v71, 0
	v_mov_b32_e32 v60, 0
	v_mov_b32_e32 v24, 0
	v_mov_b32_e32 v48, 0
	s_mov_b32 s46, 0x10000
	s_mov_b32 s47, 0
	v_mov_b32_e32 v155, v164
	v_mov_b32_e32 v165, v167
	v_mov_b32_e32 v166, v168
	s_waitcnt vmcnt(12)
	v_lshlrev_b32_e32 v136, 16, v72
	v_and_b32_e32 v137, 0xffff0000, v72
	v_lshlrev_b32_e32 v138, 16, v73
	v_and_b32_e32 v139, 0xffff0000, v73
	v_lshlrev_b32_e32 v140, 16, v74
	v_and_b32_e32 v141, 0xffff0000, v74
	v_lshlrev_b32_e32 v142, 16, v75
	v_and_b32_e32 v143, 0xffff0000, v75
	ds_write_b128 v155, v[136:139] offset:0
	ds_write_b128 v155, v[140:143] offset:80
	v_lshlrev_b32_e32 v136, 16, v76
	v_and_b32_e32 v137, 0xffff0000, v76
	v_lshlrev_b32_e32 v138, 16, v77
	v_and_b32_e32 v139, 0xffff0000, v77
	v_lshlrev_b32_e32 v140, 16, v78
	v_and_b32_e32 v141, 0xffff0000, v78
	v_lshlrev_b32_e32 v142, 16, v79
	v_and_b32_e32 v143, 0xffff0000, v79
	ds_write_b128 v155, v[136:139] offset:11264
	ds_write_b128 v155, v[140:143] offset:11344
	ds_write_b128 v165, v[80:83]
	ds_write_b128 v166, v[84:87]
	global_load_dwordx4 v[72:75], v[144:145], off
	global_load_dwordx4 v[76:79], v[146:147], off
	global_load_dwordx4 v[80:83], v[148:149], off
	global_load_dwordx4 v[84:87], v[150:151], off
	v_lshl_add_u64 v[144:145], v[144:145], 0, v[152:153]
	v_lshl_add_u64 v[146:147], v[146:147], 0, v[152:153]
	v_lshl_add_u64 v[148:149], v[148:149], 0, v[62:63]
	v_lshl_add_u64 v[150:151], v[150:151], 0, v[64:65]
	v_add_u32_e32 v155, 0x5800, v164
	v_add_u32_e32 v165, 0x5800, v167
	v_add_u32_e32 v166, 0x5800, v168
	s_waitcnt vmcnt(12)
; DEVI void rw_chain_task(const Params& p, int l, int seq, int head, int quarter, char* smem) {
;     ...
;     for (int c = 0; c < nch; c += 4) {
;       lds_barrier();
;       RW_STORE(R1, B1);
;       RW_LOAD(R1, c + 5);
;       RW_COMPUTE(B0, c);
;       lds_barrier();
;       RW_STORE(R2, B0);
;       RW_LOAD(R2, c + 6);
;       RW_COMPUTE(B1, c + 1);
;       lds_barrier();
;       RW_STORE(R3, B1);
;       RW_LOAD(R3, c + 7);
;       RW_COMPUTE(B0, c + 2);
;       lds_barrier();
;       RW_STORE(R0, B0);
;       RW_LOAD(R0, c + 8);
;       RW_COMPUTE(B1, c + 3);
;     }
	v_lshlrev_b32_e32 v136, 16, v88
	v_and_b32_e32 v137, 0xffff0000, v88
	v_lshlrev_b32_e32 v138, 16, v89
	v_and_b32_e32 v139, 0xffff0000, v89
	v_lshlrev_b32_e32 v140, 16, v90
	v_and_b32_e32 v141, 0xffff0000, v90
	v_lshlrev_b32_e32 v142, 16, v91
	v_and_b32_e32 v143, 0xffff0000, v91
	ds_write_b128 v155, v[136:139] offset:0
	ds_write_b128 v155, v[140:143] offset:80
	v_lshlrev_b32_e32 v136, 16, v92
	v_and_b32_e32 v137, 0xffff0000, v92
	v_lshlrev_b32_e32 v138, 16, v93
	v_and_b32_e32 v139, 0xffff0000, v93
	v_lshlrev_b32_e32 v140, 16, v94
	v_and_b32_e32 v141, 0xffff0000, v94
	v_lshlrev_b32_e32 v142, 16, v95
	v_and_b32_e32 v143, 0xffff0000, v95
	ds_write_b128 v155, v[136:139] offset:11264
	ds_write_b128 v155, v[140:143] offset:11344
	ds_write_b128 v165, v[96:99]
	ds_write_b128 v166, v[100:103]
	global_load_dwordx4 v[88:91], v[144:145], off
	global_load_dwordx4 v[92:95], v[146:147], off
	global_load_dwordx4 v[96:99], v[148:149], off
	global_load_dwordx4 v[100:103], v[150:151], off
	v_lshl_add_u64 v[144:145], v[144:145], 0, v[152:153]
	v_lshl_add_u64 v[146:147], v[146:147], 0, v[152:153]
	v_lshl_add_u64 v[148:149], v[148:149], 0, v[62:63]
	v_lshl_add_u64 v[150:151], v[150:151], 0, v[64:65]
	s_mov_b32 s42, 0xb000
	s_mov_b32 s43, 0
	s_mov_b32 s45, 0x5800
	s_mov_b32 s41, 0
	s_waitcnt lgkmcnt(0)
	s_barrier
	ds_read_b128 v[16:19], v162 offset:48
	ds_read_b128 v[4:7], v162 offset:0
	ds_read_b128 v[8:11], v162 offset:16
	ds_read_b128 v[12:15], v162 offset:32
	ds_read_b128 v[20:23], v162 offset:64
	ds_read_u16_d16_hi v24, v163 offset:0
.Lrwc_loop:
	s_waitcnt lgkmcnt(0)
	s_barrier
	s_mov_b32 vcc_lo, s42
	s_mov_b32 s42, s43
	s_mov_b32 s43, s45
	s_mov_b32 s45, vcc_lo
	v_add_u32_e32 v156, s42, v162
	v_add_u32_e32 v157, s42, v163
	v_add_u32_e32 v155, s45, v164
	v_add_u32_e32 v165, s45, v167
	v_add_u32_e32 v166, s45, v168
	s_waitcnt lgkmcnt(0)
	ds_read_b128 v[28:31], v156 offset:1408
	ds_read_b128 v[36:39], v156 offset:1440
	ds_read_u16_d16_hi v48, v157 offset:1408
	ds_read_b128 v[44:47], v156 offset:1472
	ds_read_b128 v[32:35], v156 offset:1424
	v_pk_mul_f32 v[172:173], v[68:69], v[4:5]
	v_pk_mul_f32 v[178:179], v[68:69], v[40:41]
	v_pk_fma_f32 v[172:173], v[70:71], v[6:7], v[172:173]
	v_pk_fma_f32 v[178:179], v[70:71], v[42:43], v[178:179]
	v_add_f32_e32 v172, v172, v173
	v_add_f32_e32 v225, v178, v179
	v_pk_mul_f32 v[52:53], v[24:25], v[12:13] op_sel_hi:[0,1]
	ds_read_b128 v[40:43], v156 offset:1456
	v_add_f32_dpp v172, v172, v172 row_ror:8 row_mask:0xf bank_mask:0xf bound_ctrl:1
	v_pk_mul_f32 v[54:55], v[24:25], v[14:15] op_sel_hi:[0,1]
	v_pk_fma_f32 v[56:57], v[68:69], v[20:21], v[52:53]
	v_add_f32_dpp v172, v172, v172 row_ror:4 row_mask:0xf bank_mask:0xf bound_ctrl:1
	v_pk_fma_f32 v[58:59], v[70:71], v[22:23], v[54:55]
	s_nop 0
	v_add_f32_dpp v172, v172, v172 row_ror:2 row_mask:0xf bank_mask:0xf bound_ctrl:1
	s_nop 1
	v_add_f32_dpp v172, v172, v172 row_ror:1 row_mask:0xf bank_mask:0xf bound_ctrl:1
	v_pk_fma_f32 v[68:69], v[172:173], v[8:9], v[56:57] op_sel_hi:[0,1,1] neg_lo:[1,0,0] neg_hi:[1,0,0]
	v_pk_fma_f32 v[70:71], v[172:173], v[10:11], v[58:59] op_sel_hi:[0,1,1] neg_lo:[1,0,0] neg_hi:[1,0,0]
	s_waitcnt lgkmcnt(0)
	ds_read_b128 v[4:7], v156 offset:2816
	ds_read_b128 v[12:15], v156 offset:2848
	ds_read_u16_d16_hi v24, v157 offset:2816
	ds_read_b128 v[20:23], v156 offset:2880
	ds_read_b128 v[8:11], v156 offset:2832
	v_pk_mul_f32 v[174:175], v[68:69], v[28:29]
	v_pk_mul_f32 v[176:177], v[68:69], v[16:17]
	v_pk_fma_f32 v[174:175], v[70:71], v[30:31], v[174:175]
	v_pk_fma_f32 v[176:177], v[70:71], v[18:19], v[176:177]
	v_add_f32_e32 v174, v174, v175
	v_add_f32_e32 v180, v176, v177
	v_pk_mul_f32 v[52:53], v[48:49], v[36:37] op_sel_hi:[0,1]
	ds_read_b128 v[16:19], v156 offset:2864
	v_add_f32_dpp v174, v174, v174 row_ror:8 row_mask:0xf bank_mask:0xf bound_ctrl:1
	v_pk_mul_f32 v[54:55], v[48:49], v[38:39] op_sel_hi:[0,1]
	v_pk_fma_f32 v[56:57], v[68:69], v[44:45], v[52:53]
	v_add_f32_dpp v174, v174, v174 row_ror:4 row_mask:0xf bank_mask:0xf bound_ctrl:1
	v_pk_fma_f32 v[58:59], v[70:71], v[46:47], v[54:55]
	s_waitcnt vmcnt(12)
	v_add_f32_dpp v174, v174, v174 row_ror:2 row_mask:0xf bank_mask:0xf bound_ctrl:1
	v_lshlrev_b32_e32 v136, 16, v104
	v_and_b32_e32 v137, 0xffff0000, v104
	v_add_f32_dpp v174, v174, v174 row_ror:1 row_mask:0xf bank_mask:0xf bound_ctrl:1
	v_add_f32_dpp v230, v196, v196 row_mirror row_mask:0xf bank_mask:0xf bound_ctrl:1
	v_add_f32_dpp v230, v212, v212 row_mirror row_mask:0xf bank_mask:0xc bound_ctrl:1
	v_pk_fma_f32 v[68:69], v[174:175], v[32:33], v[56:57] op_sel_hi:[0,1,1] neg_lo:[1,0,0] neg_hi:[1,0,0]
	v_pk_fma_f32 v[70:71], v[174:175], v[34:35], v[58:59] op_sel_hi:[0,1,1] neg_lo:[1,0,0] neg_hi:[1,0,0]
	s_waitcnt lgkmcnt(0)
	ds_read_b128 v[28:31], v156 offset:4224
	ds_read_b128 v[36:39], v156 offset:4256
	ds_read_u16_d16_hi v48, v157 offset:4224
	ds_read_b128 v[44:47], v156 offset:4288
	ds_read_b128 v[32:35], v156 offset:4240
	v_pk_mul_f32 v[172:173], v[68:69], v[4:5]
	v_pk_mul_f32 v[178:179], v[68:69], v[40:41]
	v_pk_fma_f32 v[172:173], v[70:71], v[6:7], v[172:173]
	v_pk_fma_f32 v[178:179], v[70:71], v[42:43], v[178:179]
	v_add_f32_e32 v172, v172, v173
	v_add_f32_e32 v181, v178, v179
	v_pk_mul_f32 v[52:53], v[24:25], v[12:13] op_sel_hi:[0,1]
	ds_read_b128 v[40:43], v156 offset:4272
	v_add_f32_dpp v172, v172, v172 row_ror:8 row_mask:0xf bank_mask:0xf bound_ctrl:1
	v_pk_mul_f32 v[54:55], v[24:25], v[14:15] op_sel_hi:[0,1]
	v_pk_fma_f32 v[56:57], v[68:69], v[20:21], v[52:53]
	v_add_f32_dpp v172, v172, v172 row_ror:4 row_mask:0xf bank_mask:0xf bound_ctrl:1
	v_pk_fma_f32 v[58:59], v[70:71], v[22:23], v[54:55]
	v_lshlrev_b32_e32 v138, 16, v105
	v_add_f32_dpp v172, v172, v172 row_ror:2 row_mask:0xf bank_mask:0xf bound_ctrl:1
	v_and_b32_e32 v139, 0xffff0000, v105
	v_lshlrev_b32_e32 v140, 16, v106
	v_add_f32_dpp v172, v172, v172 row_ror:1 row_mask:0xf bank_mask:0xf bound_ctrl:1
	v_add_f32_dpp v231, v197, v197 row_mirror row_mask:0xf bank_mask:0xf bound_ctrl:1
	v_add_f32_dpp v231, v213, v213 row_mirror row_mask:0xf bank_mask:0xc bound_ctrl:1
	v_pk_fma_f32 v[68:69], v[172:173], v[8:9], v[56:57] op_sel_hi:[0,1,1] neg_lo:[1,0,0] neg_hi:[1,0,0]
	v_pk_fma_f32 v[70:71], v[172:173], v[10:11], v[58:59] op_sel_hi:[0,1,1] neg_lo:[1,0,0] neg_hi:[1,0,0]
	s_waitcnt lgkmcnt(0)
	ds_read_b128 v[4:7], v156 offset:5632
	ds_read_b128 v[12:15], v156 offset:5664
	ds_read_u16_d16_hi v24, v157 offset:5632
	ds_read_b128 v[20:23], v156 offset:5696
	ds_read_b128 v[8:11], v156 offset:5648
	v_pk_mul_f32 v[174:175], v[68:69], v[28:29]
	v_pk_mul_f32 v[176:177], v[68:69], v[16:17]
	v_pk_fma_f32 v[174:175], v[70:71], v[30:31], v[174:175]
	v_pk_fma_f32 v[176:177], v[70:71], v[18:19], v[176:177]
	v_add_f32_e32 v174, v174, v175
	v_add_f32_e32 v182, v176, v177
	v_pk_mul_f32 v[52:53], v[48:49], v[36:37] op_sel_hi:[0,1]
	ds_read_b128 v[16:19], v156 offset:5680
	v_add_f32_dpp v174, v174, v174 row_ror:8 row_mask:0xf bank_mask:0xf bound_ctrl:1
	v_pk_mul_f32 v[54:55], v[48:49], v[38:39] op_sel_hi:[0,1]
	v_pk_fma_f32 v[56:57], v[68:69], v[44:45], v[52:53]
	v_add_f32_dpp v174, v174, v174 row_ror:4 row_mask:0xf bank_mask:0xf bound_ctrl:1
	v_pk_fma_f32 v[58:59], v[70:71], v[46:47], v[54:55]
	v_and_b32_e32 v141, 0xffff0000, v106
	v_add_f32_dpp v174, v174, v174 row_ror:2 row_mask:0xf bank_mask:0xf bound_ctrl:1
	v_lshlrev_b32_e32 v142, 16, v107
	v_and_b32_e32 v143, 0xffff0000, v107
	v_add_f32_dpp v174, v174, v174 row_ror:1 row_mask:0xf bank_mask:0xf bound_ctrl:1
	v_add_f32_dpp v232, v198, v198 row_mirror row_mask:0xf bank_mask:0xf bound_ctrl:1
	v_add_f32_dpp v232, v220, v220 row_mirror row_mask:0xf bank_mask:0xc bound_ctrl:1
	v_pk_fma_f32 v[68:69], v[174:175], v[32:33], v[56:57] op_sel_hi:[0,1,1] neg_lo:[1,0,0] neg_hi:[1,0,0]
	v_pk_fma_f32 v[70:71], v[174:175], v[34:35], v[58:59] op_sel_hi:[0,1,1] neg_lo:[1,0,0] neg_hi:[1,0,0]
	s_waitcnt lgkmcnt(0)
	ds_read_b128 v[28:31], v156 offset:7040
	ds_read_b128 v[36:39], v156 offset:7072
	ds_read_u16_d16_hi v48, v157 offset:7040
	ds_read_b128 v[44:47], v156 offset:7104
	ds_read_b128 v[32:35], v156 offset:7056
	v_pk_mul_f32 v[172:173], v[68:69], v[4:5]
	v_pk_mul_f32 v[178:179], v[68:69], v[40:41]
	v_pk_fma_f32 v[172:173], v[70:71], v[6:7], v[172:173]
	v_pk_fma_f32 v[178:179], v[70:71], v[42:43], v[178:179]
	v_add_f32_e32 v172, v172, v173
	v_add_f32_e32 v183, v178, v179
	v_pk_mul_f32 v[52:53], v[24:25], v[12:13] op_sel_hi:[0,1]
	ds_read_b128 v[40:43], v156 offset:7088
	v_add_f32_dpp v172, v172, v172 row_ror:8 row_mask:0xf bank_mask:0xf bound_ctrl:1
	v_pk_mul_f32 v[54:55], v[24:25], v[14:15] op_sel_hi:[0,1]
	v_pk_fma_f32 v[56:57], v[68:69], v[20:21], v[52:53]
	v_add_f32_dpp v172, v172, v172 row_ror:4 row_mask:0xf bank_mask:0xf bound_ctrl:1
	v_pk_fma_f32 v[58:59], v[70:71], v[22:23], v[54:55]
	ds_write_b128 v155, v[136:139] offset:0
	v_add_f32_dpp v172, v172, v172 row_ror:2 row_mask:0xf bank_mask:0xf bound_ctrl:1
	ds_write_b128 v155, v[140:143] offset:80
	v_lshlrev_b32_e32 v136, 16, v108
	v_add_f32_dpp v172, v172, v172 row_ror:1 row_mask:0xf bank_mask:0xf bound_ctrl:1
	v_add_f32_dpp v233, v199, v199 row_mirror row_mask:0xf bank_mask:0xf bound_ctrl:1
	v_add_f32_dpp v233, v221, v221 row_mirror row_mask:0xf bank_mask:0xc bound_ctrl:1
	v_pk_fma_f32 v[68:69], v[172:173], v[8:9], v[56:57] op_sel_hi:[0,1,1] neg_lo:[1,0,0] neg_hi:[1,0,0]
	v_pk_fma_f32 v[70:71], v[172:173], v[10:11], v[58:59] op_sel_hi:[0,1,1] neg_lo:[1,0,0] neg_hi:[1,0,0]
	v_add_f32_dpp v234, v200, v200 row_mirror row_mask:0xf bank_mask:0xf bound_ctrl:1
	s_waitcnt lgkmcnt(2)
	ds_read_b128 v[4:7], v156 offset:8448
	ds_read_b128 v[12:15], v156 offset:8480
	ds_read_u16_d16_hi v24, v157 offset:8448
	ds_read_b128 v[20:23], v156 offset:8512
	ds_read_b128 v[8:11], v156 offset:8464
	v_pk_mul_f32 v[174:175], v[68:69], v[28:29]
	v_pk_mul_f32 v[176:177], v[68:69], v[16:17]
	v_pk_fma_f32 v[174:175], v[70:71], v[30:31], v[174:175]
	v_pk_fma_f32 v[176:177], v[70:71], v[18:19], v[176:177]
	v_add_f32_e32 v174, v174, v175
	v_add_f32_e32 v184, v176, v177
	v_pk_mul_f32 v[52:53], v[48:49], v[36:37] op_sel_hi:[0,1]
	ds_read_b128 v[16:19], v156 offset:8496
	v_add_f32_dpp v174, v174, v174 row_ror:8 row_mask:0xf bank_mask:0xf bound_ctrl:1
	v_pk_mul_f32 v[54:55], v[48:49], v[38:39] op_sel_hi:[0,1]
	v_pk_fma_f32 v[56:57], v[68:69], v[44:45], v[52:53]
	v_add_f32_dpp v174, v174, v174 row_ror:4 row_mask:0xf bank_mask:0xf bound_ctrl:1
	v_pk_fma_f32 v[58:59], v[70:71], v[46:47], v[54:55]
	v_and_b32_e32 v137, 0xffff0000, v108
	v_add_f32_dpp v174, v174, v174 row_ror:2 row_mask:0xf bank_mask:0xf bound_ctrl:1
	v_lshlrev_b32_e32 v138, 16, v109
	v_and_b32_e32 v139, 0xffff0000, v109
	v_add_f32_dpp v174, v174, v174 row_ror:1 row_mask:0xf bank_mask:0xf bound_ctrl:1
	v_add_f32_dpp v234, v222, v222 row_mirror row_mask:0xf bank_mask:0xc bound_ctrl:1
	v_add_f32_dpp v235, v201, v201 row_mirror row_mask:0xf bank_mask:0xf bound_ctrl:1
	v_pk_fma_f32 v[68:69], v[174:175], v[32:33], v[56:57] op_sel_hi:[0,1,1] neg_lo:[1,0,0] neg_hi:[1,0,0]
	v_pk_fma_f32 v[70:71], v[174:175], v[34:35], v[58:59] op_sel_hi:[0,1,1] neg_lo:[1,0,0] neg_hi:[1,0,0]
	s_waitcnt lgkmcnt(0)
	ds_read_b128 v[28:31], v156 offset:9856
	ds_read_b128 v[36:39], v156 offset:9888
	ds_read_u16_d16_hi v48, v157 offset:9856
	ds_read_b128 v[44:47], v156 offset:9920
	ds_read_b128 v[32:35], v156 offset:9872
	v_pk_mul_f32 v[172:173], v[68:69], v[4:5]
	v_pk_mul_f32 v[178:179], v[68:69], v[40:41]
	v_pk_fma_f32 v[172:173], v[70:71], v[6:7], v[172:173]
	v_pk_fma_f32 v[178:179], v[70:71], v[42:43], v[178:179]
	v_add_f32_e32 v172, v172, v173
	v_add_f32_e32 v185, v178, v179
	v_pk_mul_f32 v[52:53], v[24:25], v[12:13] op_sel_hi:[0,1]
	ds_read_b128 v[40:43], v156 offset:9904
	v_add_f32_dpp v172, v172, v172 row_ror:8 row_mask:0xf bank_mask:0xf bound_ctrl:1
	v_pk_mul_f32 v[54:55], v[24:25], v[14:15] op_sel_hi:[0,1]
	v_pk_fma_f32 v[56:57], v[68:69], v[20:21], v[52:53]
	v_add_f32_dpp v172, v172, v172 row_ror:4 row_mask:0xf bank_mask:0xf bound_ctrl:1
	v_pk_fma_f32 v[58:59], v[70:71], v[22:23], v[54:55]
	v_lshlrev_b32_e32 v140, 16, v110
	v_add_f32_dpp v172, v172, v172 row_ror:2 row_mask:0xf bank_mask:0xf bound_ctrl:1
	v_and_b32_e32 v141, 0xffff0000, v110
	v_lshlrev_b32_e32 v142, 16, v111
	v_add_f32_dpp v172, v172, v172 row_ror:1 row_mask:0xf bank_mask:0xf bound_ctrl:1
	v_add_f32_dpp v235, v223, v223 row_mirror row_mask:0xf bank_mask:0xc bound_ctrl:1
	v_add_f32_dpp v236, v210, v210 row_mirror row_mask:0xf bank_mask:0xf bound_ctrl:1
	v_pk_fma_f32 v[68:69], v[172:173], v[8:9], v[56:57] op_sel_hi:[0,1,1] neg_lo:[1,0,0] neg_hi:[1,0,0]
	v_pk_fma_f32 v[70:71], v[172:173], v[10:11], v[58:59] op_sel_hi:[0,1,1] neg_lo:[1,0,0] neg_hi:[1,0,0]
	s_waitcnt lgkmcnt(0)
	ds_read_b128 v[4:7], v156 offset:11264
	ds_read_b128 v[12:15], v156 offset:11296
	ds_read_u16_d16_hi v24, v157 offset:11264
	ds_read_b128 v[20:23], v156 offset:11328
	ds_read_b128 v[8:11], v156 offset:11280
	v_pk_mul_f32 v[174:175], v[68:69], v[28:29]
	v_pk_mul_f32 v[176:177], v[68:69], v[16:17]
	v_pk_fma_f32 v[174:175], v[70:71], v[30:31], v[174:175]
	v_pk_fma_f32 v[176:177], v[70:71], v[18:19], v[176:177]
	v_add_f32_e32 v174, v174, v175
	v_add_f32_e32 v186, v176, v177
	v_pk_mul_f32 v[52:53], v[48:49], v[36:37] op_sel_hi:[0,1]
	ds_read_b128 v[16:19], v156 offset:11312
	v_add_f32_dpp v174, v174, v174 row_ror:8 row_mask:0xf bank_mask:0xf bound_ctrl:1
	v_pk_mul_f32 v[54:55], v[48:49], v[38:39] op_sel_hi:[0,1]
	v_pk_fma_f32 v[56:57], v[68:69], v[44:45], v[52:53]
	v_add_f32_dpp v174, v174, v174 row_ror:4 row_mask:0xf bank_mask:0xf bound_ctrl:1
	v_pk_fma_f32 v[58:59], v[70:71], v[46:47], v[54:55]
	v_and_b32_e32 v143, 0xffff0000, v111
	v_add_f32_dpp v174, v174, v174 row_ror:2 row_mask:0xf bank_mask:0xf bound_ctrl:1
	ds_write_b128 v155, v[136:139] offset:11264
	ds_write_b128 v155, v[140:143] offset:11344
	v_add_f32_dpp v174, v174, v174 row_ror:1 row_mask:0xf bank_mask:0xf bound_ctrl:1
	v_add_f32_dpp v236, v224, v224 row_mirror row_mask:0xf bank_mask:0xc bound_ctrl:1
	v_add_f32_dpp v237, v211, v211 row_mirror row_mask:0xf bank_mask:0xf bound_ctrl:1
	v_pk_fma_f32 v[68:69], v[174:175], v[32:33], v[56:57] op_sel_hi:[0,1,1] neg_lo:[1,0,0] neg_hi:[1,0,0]
	v_pk_fma_f32 v[70:71], v[174:175], v[34:35], v[58:59] op_sel_hi:[0,1,1] neg_lo:[1,0,0] neg_hi:[1,0,0]
	s_waitcnt lgkmcnt(2)
	ds_read_b128 v[28:31], v156 offset:12672
	ds_read_b128 v[36:39], v156 offset:12704
	ds_read_u16_d16_hi v48, v157 offset:12672
	ds_read_b128 v[44:47], v156 offset:12736
	ds_read_b128 v[32:35], v156 offset:12688
	v_pk_mul_f32 v[172:173], v[68:69], v[4:5]
	v_pk_mul_f32 v[178:179], v[68:69], v[40:41]
	v_pk_fma_f32 v[172:173], v[70:71], v[6:7], v[172:173]
	v_pk_fma_f32 v[178:179], v[70:71], v[42:43], v[178:179]
	v_add_f32_e32 v172, v172, v173
	v_add_f32_e32 v187, v178, v179
	v_pk_mul_f32 v[52:53], v[24:25], v[12:13] op_sel_hi:[0,1]
	ds_read_b128 v[40:43], v156 offset:12720
	v_add_f32_dpp v172, v172, v172 row_ror:8 row_mask:0xf bank_mask:0xf bound_ctrl:1
	v_pk_mul_f32 v[54:55], v[24:25], v[14:15] op_sel_hi:[0,1]
	v_pk_fma_f32 v[56:57], v[68:69], v[20:21], v[52:53]
	v_add_f32_dpp v172, v172, v172 row_ror:4 row_mask:0xf bank_mask:0xf bound_ctrl:1
	v_pk_fma_f32 v[58:59], v[70:71], v[22:23], v[54:55]
	ds_write_b128 v165, v[112:115]
	v_add_f32_dpp v172, v172, v172 row_ror:2 row_mask:0xf bank_mask:0xf bound_ctrl:1
	ds_write_b128 v166, v[116:119]
	global_load_dwordx4 v[104:107], v[144:145], off
	v_add_f32_dpp v172, v172, v172 row_ror:1 row_mask:0xf bank_mask:0xf bound_ctrl:1
	v_add_f32_dpp v237, v225, v225 row_mirror row_mask:0xf bank_mask:0xc bound_ctrl:1
	v_add_f32_dpp v238, v230, v230 row_half_mirror row_mask:0xf bank_mask:0xf bound_ctrl:1
	v_pk_fma_f32 v[68:69], v[172:173], v[8:9], v[56:57] op_sel_hi:[0,1,1] neg_lo:[1,0,0] neg_hi:[1,0,0]
	v_pk_fma_f32 v[70:71], v[172:173], v[10:11], v[58:59] op_sel_hi:[0,1,1] neg_lo:[1,0,0] neg_hi:[1,0,0]
	v_add_f32_dpp v238, v234, v234 row_half_mirror row_mask:0xf bank_mask:0xa bound_ctrl:1
	s_waitcnt lgkmcnt(2)
	ds_read_b128 v[4:7], v156 offset:14080
	ds_read_b128 v[12:15], v156 offset:14112
	ds_read_u16_d16_hi v24, v157 offset:14080
	ds_read_b128 v[20:23], v156 offset:14144
	ds_read_b128 v[8:11], v156 offset:14096
	v_pk_mul_f32 v[174:175], v[68:69], v[28:29]
	v_pk_mul_f32 v[176:177], v[68:69], v[16:17]
	v_pk_fma_f32 v[174:175], v[70:71], v[30:31], v[174:175]
	v_pk_fma_f32 v[176:177], v[70:71], v[18:19], v[176:177]
	v_add_f32_e32 v174, v174, v175
	v_add_f32_e32 v188, v176, v177
	v_pk_mul_f32 v[52:53], v[48:49], v[36:37] op_sel_hi:[0,1]
	ds_read_b128 v[16:19], v156 offset:14128
	v_add_f32_dpp v174, v174, v174 row_ror:8 row_mask:0xf bank_mask:0xf bound_ctrl:1
	v_pk_mul_f32 v[54:55], v[48:49], v[38:39] op_sel_hi:[0,1]
	v_pk_fma_f32 v[56:57], v[68:69], v[44:45], v[52:53]
	v_add_f32_dpp v174, v174, v174 row_ror:4 row_mask:0xf bank_mask:0xf bound_ctrl:1
	v_pk_fma_f32 v[58:59], v[70:71], v[46:47], v[54:55]
	global_load_dwordx4 v[108:111], v[146:147], off
	v_add_f32_dpp v174, v174, v174 row_ror:2 row_mask:0xf bank_mask:0xf bound_ctrl:1
	global_load_dwordx4 v[112:115], v[148:149], off
	global_load_dwordx4 v[116:119], v[150:151], off
	v_add_f32_dpp v174, v174, v174 row_ror:1 row_mask:0xf bank_mask:0xf bound_ctrl:1
	v_add_f32_dpp v239, v231, v231 row_half_mirror row_mask:0xf bank_mask:0xf bound_ctrl:1
	v_add_f32_dpp v239, v235, v235 row_half_mirror row_mask:0xf bank_mask:0xa bound_ctrl:1
	v_pk_fma_f32 v[68:69], v[174:175], v[32:33], v[56:57] op_sel_hi:[0,1,1] neg_lo:[1,0,0] neg_hi:[1,0,0]
	v_pk_fma_f32 v[70:71], v[174:175], v[34:35], v[58:59] op_sel_hi:[0,1,1] neg_lo:[1,0,0] neg_hi:[1,0,0]
	s_waitcnt lgkmcnt(0)
	ds_read_b128 v[28:31], v156 offset:15488
	ds_read_b128 v[36:39], v156 offset:15520
	ds_read_u16_d16_hi v48, v157 offset:15488
	ds_read_b128 v[44:47], v156 offset:15552
	ds_read_b128 v[32:35], v156 offset:15504
	v_pk_mul_f32 v[172:173], v[68:69], v[4:5]
	v_pk_mul_f32 v[178:179], v[68:69], v[40:41]
	v_pk_fma_f32 v[172:173], v[70:71], v[6:7], v[172:173]
	v_pk_fma_f32 v[178:179], v[70:71], v[42:43], v[178:179]
	v_add_f32_e32 v172, v172, v173
	v_add_f32_e32 v189, v178, v179
	v_pk_mul_f32 v[52:53], v[24:25], v[12:13] op_sel_hi:[0,1]
	ds_read_b128 v[40:43], v156 offset:15536
	v_add_f32_dpp v172, v172, v172 row_ror:8 row_mask:0xf bank_mask:0xf bound_ctrl:1
	v_pk_mul_f32 v[54:55], v[24:25], v[14:15] op_sel_hi:[0,1]
	v_pk_fma_f32 v[56:57], v[68:69], v[20:21], v[52:53]
	v_add_f32_dpp v172, v172, v172 row_ror:4 row_mask:0xf bank_mask:0xf bound_ctrl:1
	v_pk_fma_f32 v[58:59], v[70:71], v[22:23], v[54:55]
	v_lshl_add_u64 v[144:145], v[144:145], 0, v[152:153]
	v_add_f32_dpp v172, v172, v172 row_ror:2 row_mask:0xf bank_mask:0xf bound_ctrl:1
	v_lshl_add_u64 v[146:147], v[146:147], 0, v[152:153]
	v_lshl_add_u64 v[148:149], v[148:149], 0, v[62:63]
	v_add_f32_dpp v172, v172, v172 row_ror:1 row_mask:0xf bank_mask:0xf bound_ctrl:1
	v_add_f32_dpp v240, v232, v232 row_half_mirror row_mask:0xf bank_mask:0xf bound_ctrl:1
	v_add_f32_dpp v240, v236, v236 row_half_mirror row_mask:0xf bank_mask:0xa bound_ctrl:1
	v_pk_fma_f32 v[68:69], v[172:173], v[8:9], v[56:57] op_sel_hi:[0,1,1] neg_lo:[1,0,0] neg_hi:[1,0,0]
	v_pk_fma_f32 v[70:71], v[172:173], v[10:11], v[58:59] op_sel_hi:[0,1,1] neg_lo:[1,0,0] neg_hi:[1,0,0]
	s_waitcnt lgkmcnt(0)
	ds_read_b128 v[4:7], v156 offset:16896
	ds_read_b128 v[12:15], v156 offset:16928
	ds_read_u16_d16_hi v24, v157 offset:16896
	ds_read_b128 v[20:23], v156 offset:16960
	ds_read_b128 v[8:11], v156 offset:16912
	v_pk_mul_f32 v[174:175], v[68:69], v[28:29]
	v_pk_mul_f32 v[176:177], v[68:69], v[16:17]
	v_pk_fma_f32 v[174:175], v[70:71], v[30:31], v[174:175]
	v_pk_fma_f32 v[176:177], v[70:71], v[18:19], v[176:177]
	v_add_f32_e32 v174, v174, v175
	v_add_f32_e32 v190, v176, v177
	v_pk_mul_f32 v[52:53], v[48:49], v[36:37] op_sel_hi:[0,1]
	ds_read_b128 v[16:19], v156 offset:16944
	v_add_f32_dpp v174, v174, v174 row_ror:8 row_mask:0xf bank_mask:0xf bound_ctrl:1
	v_pk_mul_f32 v[54:55], v[48:49], v[38:39] op_sel_hi:[0,1]
	v_pk_fma_f32 v[56:57], v[68:69], v[44:45], v[52:53]
	v_add_f32_dpp v174, v174, v174 row_ror:4 row_mask:0xf bank_mask:0xf bound_ctrl:1
	v_pk_fma_f32 v[58:59], v[70:71], v[46:47], v[54:55]
	v_lshl_add_u64 v[150:151], v[150:151], 0, v[64:65]
	v_add_f32_dpp v174, v174, v174 row_ror:2 row_mask:0xf bank_mask:0xf bound_ctrl:1
	v_add_u32_e32 v158, s43, v162
	v_add_u32_e32 v159, s43, v163
	v_add_f32_dpp v174, v174, v174 row_ror:1 row_mask:0xf bank_mask:0xf bound_ctrl:1
	v_add_f32_dpp v241, v233, v233 row_half_mirror row_mask:0xf bank_mask:0xf bound_ctrl:1
	v_add_f32_dpp v241, v237, v237 row_half_mirror row_mask:0xf bank_mask:0xa bound_ctrl:1
	v_pk_fma_f32 v[68:69], v[174:175], v[32:33], v[56:57] op_sel_hi:[0,1,1] neg_lo:[1,0,0] neg_hi:[1,0,0]
	v_pk_fma_f32 v[70:71], v[174:175], v[34:35], v[58:59] op_sel_hi:[0,1,1] neg_lo:[1,0,0] neg_hi:[1,0,0]
	s_waitcnt lgkmcnt(0)
	ds_read_b128 v[28:31], v156 offset:18304
	ds_read_b128 v[36:39], v156 offset:18336
	ds_read_u16_d16_hi v48, v157 offset:18304
	ds_read_b128 v[44:47], v156 offset:18368
	ds_read_b128 v[32:35], v156 offset:18320
	v_pk_mul_f32 v[172:173], v[68:69], v[4:5]
	v_pk_mul_f32 v[178:179], v[68:69], v[40:41]
	v_pk_fma_f32 v[172:173], v[70:71], v[6:7], v[172:173]
	v_pk_fma_f32 v[178:179], v[70:71], v[42:43], v[178:179]
	v_add_f32_e32 v172, v172, v173
	v_add_f32_e32 v191, v178, v179
	v_pk_mul_f32 v[52:53], v[24:25], v[12:13] op_sel_hi:[0,1]
	ds_read_b128 v[40:43], v156 offset:18352
	v_add_f32_dpp v172, v172, v172 row_ror:8 row_mask:0xf bank_mask:0xf bound_ctrl:1
	v_pk_mul_f32 v[54:55], v[24:25], v[14:15] op_sel_hi:[0,1]
	v_pk_fma_f32 v[56:57], v[68:69], v[20:21], v[52:53]
	v_add_f32_dpp v172, v172, v172 row_ror:4 row_mask:0xf bank_mask:0xf bound_ctrl:1
	v_pk_fma_f32 v[58:59], v[70:71], v[22:23], v[54:55]
	v_add_f32_dpp v242, v238, v238 quad_perm:[3,2,1,0] row_mask:0xf bank_mask:0xf bound_ctrl:1
	v_add_f32_dpp v172, v172, v172 row_ror:2 row_mask:0xf bank_mask:0xf bound_ctrl:1
	v_add_f32_dpp v243, v240, v240 quad_perm:[3,2,1,0] row_mask:0xf bank_mask:0xf bound_ctrl:1
	v_cndmask_b32_e64 v244, v242, v243, s[4:5]
	v_add_f32_dpp v172, v172, v172 row_ror:1 row_mask:0xf bank_mask:0xf bound_ctrl:1
	v_pk_fma_f32 v[68:69], v[172:173], v[8:9], v[56:57] op_sel_hi:[0,1,1] neg_lo:[1,0,0] neg_hi:[1,0,0]
	v_pk_fma_f32 v[70:71], v[172:173], v[10:11], v[58:59] op_sel_hi:[0,1,1] neg_lo:[1,0,0] neg_hi:[1,0,0]
	s_waitcnt lgkmcnt(0)
	ds_read_b128 v[4:7], v156 offset:19712
	ds_read_b128 v[12:15], v156 offset:19744
	ds_read_u16_d16_hi v24, v157 offset:19712
	ds_read_b128 v[20:23], v156 offset:19776
	ds_read_b128 v[8:11], v156 offset:19728
	v_pk_mul_f32 v[174:175], v[68:69], v[28:29]
	v_pk_mul_f32 v[176:177], v[68:69], v[16:17]
	v_pk_fma_f32 v[174:175], v[70:71], v[30:31], v[174:175]
	v_pk_fma_f32 v[176:177], v[70:71], v[18:19], v[176:177]
	v_add_f32_e32 v174, v174, v175
	v_add_f32_e32 v192, v176, v177
	v_pk_mul_f32 v[52:53], v[48:49], v[36:37] op_sel_hi:[0,1]
	ds_read_b128 v[16:19], v156 offset:19760
	v_add_f32_dpp v174, v174, v174 row_ror:8 row_mask:0xf bank_mask:0xf bound_ctrl:1
	v_pk_mul_f32 v[54:55], v[48:49], v[38:39] op_sel_hi:[0,1]
	v_pk_fma_f32 v[56:57], v[68:69], v[44:45], v[52:53]
	v_add_f32_dpp v174, v174, v174 row_ror:4 row_mask:0xf bank_mask:0xf bound_ctrl:1
	v_pk_fma_f32 v[58:59], v[70:71], v[46:47], v[54:55]
	v_add_f32_dpp v242, v239, v239 quad_perm:[3,2,1,0] row_mask:0xf bank_mask:0xf bound_ctrl:1
	v_add_f32_dpp v174, v174, v174 row_ror:2 row_mask:0xf bank_mask:0xf bound_ctrl:1
	v_add_f32_dpp v243, v241, v241 quad_perm:[3,2,1,0] row_mask:0xf bank_mask:0xf bound_ctrl:1
	s_nop 0
	v_add_f32_dpp v174, v174, v174 row_ror:1 row_mask:0xf bank_mask:0xf bound_ctrl:1
	v_pk_fma_f32 v[68:69], v[174:175], v[32:33], v[56:57] op_sel_hi:[0,1,1] neg_lo:[1,0,0] neg_hi:[1,0,0]
	v_pk_fma_f32 v[70:71], v[174:175], v[34:35], v[58:59] op_sel_hi:[0,1,1] neg_lo:[1,0,0] neg_hi:[1,0,0]
	s_waitcnt lgkmcnt(0)
; DEVI void rw_chain_task(const Params& p, int l, int seq, int head, int quarter, char* smem) {
;     ...
;     for (int c = 0; c < nch; c += 4) {
;       lds_barrier();
;       RW_STORE(R1, B1);
;       RW_LOAD(R1, c + 5);
;       RW_COMPUTE(B0, c);
;       lds_barrier();
;       RW_STORE(R2, B0);
;       RW_LOAD(R2, c + 6);
;       RW_COMPUTE(B1, c + 1);
;       lds_barrier();
;       RW_STORE(R3, B1);
;       RW_LOAD(R3, c + 7);
;       RW_COMPUTE(B0, c + 2);
;       lds_barrier();
;       RW_STORE(R0, B0);
;       RW_LOAD(R0, c + 8);
;       RW_COMPUTE(B1, c + 3);
;     }
	ds_read_b128 v[28:31], v156 offset:21120
	ds_read_b128 v[36:39], v156 offset:21152
	ds_read_u16_d16_hi v48, v157 offset:21120
	ds_read_b128 v[44:47], v156 offset:21184
	ds_read_b128 v[32:35], v156 offset:21136
	v_pk_mul_f32 v[172:173], v[68:69], v[4:5]
	v_pk_mul_f32 v[178:179], v[68:69], v[40:41]
	v_pk_fma_f32 v[172:173], v[70:71], v[6:7], v[172:173]
	v_pk_fma_f32 v[178:179], v[70:71], v[42:43], v[178:179]
	v_add_f32_e32 v172, v172, v173
	v_add_f32_e32 v193, v178, v179
	v_pk_mul_f32 v[52:53], v[24:25], v[12:13] op_sel_hi:[0,1]
	ds_read_b128 v[40:43], v156 offset:21168
	v_add_f32_dpp v172, v172, v172 row_ror:8 row_mask:0xf bank_mask:0xf bound_ctrl:1
	v_pk_mul_f32 v[54:55], v[24:25], v[14:15] op_sel_hi:[0,1]
	v_pk_fma_f32 v[56:57], v[68:69], v[20:21], v[52:53]
	v_add_f32_dpp v172, v172, v172 row_ror:4 row_mask:0xf bank_mask:0xf bound_ctrl:1
	v_pk_fma_f32 v[58:59], v[70:71], v[22:23], v[54:55]
	v_cndmask_b32_e64 v245, v242, v243, s[4:5]
	v_add_f32_dpp v172, v172, v172 row_ror:2 row_mask:0xf bank_mask:0xf bound_ctrl:1
	v_add_f32_dpp v242, v244, v244 quad_perm:[1,0,3,2] row_mask:0xf bank_mask:0xf bound_ctrl:1
	s_nop 0
	v_add_f32_dpp v172, v172, v172 row_ror:1 row_mask:0xf bank_mask:0xf bound_ctrl:1
	v_pk_fma_f32 v[68:69], v[172:173], v[8:9], v[56:57] op_sel_hi:[0,1,1] neg_lo:[1,0,0] neg_hi:[1,0,0]
	v_pk_fma_f32 v[70:71], v[172:173], v[10:11], v[58:59] op_sel_hi:[0,1,1] neg_lo:[1,0,0] neg_hi:[1,0,0]
	s_waitcnt lgkmcnt(0)
	ds_read_b128 v[4:7], v158 offset:0
	ds_read_b128 v[12:15], v158 offset:32
	ds_read_u16_d16_hi v24, v159 offset:0
	ds_read_b128 v[20:23], v158 offset:64
	ds_read_b128 v[8:11], v158 offset:16
	v_pk_mul_f32 v[174:175], v[68:69], v[28:29]
	v_pk_mul_f32 v[176:177], v[68:69], v[16:17]
	v_pk_fma_f32 v[174:175], v[70:71], v[30:31], v[174:175]
	v_pk_fma_f32 v[176:177], v[70:71], v[18:19], v[176:177]
	v_add_f32_e32 v174, v174, v175
	v_add_f32_e32 v194, v176, v177
	v_pk_mul_f32 v[52:53], v[48:49], v[36:37] op_sel_hi:[0,1]
	ds_read_b128 v[16:19], v158 offset:48
	v_add_f32_dpp v174, v174, v174 row_ror:8 row_mask:0xf bank_mask:0xf bound_ctrl:1
	v_pk_mul_f32 v[54:55], v[48:49], v[38:39] op_sel_hi:[0,1]
	v_pk_fma_f32 v[56:57], v[68:69], v[44:45], v[52:53]
	v_add_f32_dpp v174, v174, v174 row_ror:4 row_mask:0xf bank_mask:0xf bound_ctrl:1
	v_pk_fma_f32 v[58:59], v[70:71], v[46:47], v[54:55]
	v_add_f32_dpp v243, v245, v245 quad_perm:[1,0,3,2] row_mask:0xf bank_mask:0xf bound_ctrl:1
	v_add_f32_dpp v174, v174, v174 row_ror:2 row_mask:0xf bank_mask:0xf bound_ctrl:1
	v_cndmask_b32_e64 v246, v242, v243, s[6:7]
	s_cmp_eq_u32 s41, 0
	s_cbranch_scc1 .Lrwc_nostore
	v_bfe_u32 v61, v246, 16, 1
	v_add3_u32 v61, v246, v61, s33
	global_store_short_d16_hi v[160:161], v61, off
	v_lshl_add_u64 v[160:161], v[160:161], 0, s[46:47]
.Lrwc_nostore:
	v_add_f32_dpp v174, v174, v174 row_ror:1 row_mask:0xf bank_mask:0xf bound_ctrl:1
	v_pk_fma_f32 v[68:69], v[174:175], v[32:33], v[56:57] op_sel_hi:[0,1,1] neg_lo:[1,0,0] neg_hi:[1,0,0]
	v_pk_fma_f32 v[70:71], v[174:175], v[34:35], v[58:59] op_sel_hi:[0,1,1] neg_lo:[1,0,0] neg_hi:[1,0,0]
	s_waitcnt lgkmcnt(0)
	s_barrier
	s_mov_b32 vcc_lo, s42
	s_mov_b32 s42, s43
	s_mov_b32 s43, s45
	s_mov_b32 s45, vcc_lo
	v_add_u32_e32 v156, s42, v162
	v_add_u32_e32 v157, s42, v163
	v_add_u32_e32 v155, s45, v164
	v_add_u32_e32 v165, s45, v167
	v_add_u32_e32 v166, s45, v168
	s_waitcnt lgkmcnt(0)
	ds_read_b128 v[28:31], v156 offset:1408
	ds_read_b128 v[36:39], v156 offset:1440
	ds_read_u16_d16_hi v48, v157 offset:1408
	ds_read_b128 v[44:47], v156 offset:1472
	ds_read_b128 v[32:35], v156 offset:1424
	v_pk_mul_f32 v[172:173], v[68:69], v[4:5]
	v_pk_mul_f32 v[178:179], v[68:69], v[40:41]
	v_pk_fma_f32 v[172:173], v[70:71], v[6:7], v[172:173]
	v_pk_fma_f32 v[178:179], v[70:71], v[42:43], v[178:179]
	v_add_f32_e32 v172, v172, v173
	v_add_f32_e32 v195, v178, v179
	v_pk_mul_f32 v[52:53], v[24:25], v[12:13] op_sel_hi:[0,1]
	ds_read_b128 v[40:43], v156 offset:1456
	v_add_f32_dpp v172, v172, v172 row_ror:8 row_mask:0xf bank_mask:0xf bound_ctrl:1
	v_pk_mul_f32 v[54:55], v[24:25], v[14:15] op_sel_hi:[0,1]
	v_pk_fma_f32 v[56:57], v[68:69], v[20:21], v[52:53]
	v_add_f32_dpp v172, v172, v172 row_ror:4 row_mask:0xf bank_mask:0xf bound_ctrl:1
	v_pk_fma_f32 v[58:59], v[70:71], v[22:23], v[54:55]
	s_nop 0
	v_add_f32_dpp v172, v172, v172 row_ror:2 row_mask:0xf bank_mask:0xf bound_ctrl:1
	s_nop 1
	v_add_f32_dpp v172, v172, v172 row_ror:1 row_mask:0xf bank_mask:0xf bound_ctrl:1
	v_pk_fma_f32 v[68:69], v[172:173], v[8:9], v[56:57] op_sel_hi:[0,1,1] neg_lo:[1,0,0] neg_hi:[1,0,0]
	v_pk_fma_f32 v[70:71], v[172:173], v[10:11], v[58:59] op_sel_hi:[0,1,1] neg_lo:[1,0,0] neg_hi:[1,0,0]
	s_waitcnt lgkmcnt(0)
	ds_read_b128 v[4:7], v156 offset:2816
	ds_read_b128 v[12:15], v156 offset:2848
	ds_read_u16_d16_hi v24, v157 offset:2816
	ds_read_b128 v[20:23], v156 offset:2880
	ds_read_b128 v[8:11], v156 offset:2832
	v_pk_mul_f32 v[174:175], v[68:69], v[28:29]
	v_pk_mul_f32 v[176:177], v[68:69], v[16:17]
	v_pk_fma_f32 v[174:175], v[70:71], v[30:31], v[174:175]
	v_pk_fma_f32 v[176:177], v[70:71], v[18:19], v[176:177]
	v_add_f32_e32 v174, v174, v175
	v_add_f32_e32 v196, v176, v177
	v_pk_mul_f32 v[52:53], v[48:49], v[36:37] op_sel_hi:[0,1]
	ds_read_b128 v[16:19], v156 offset:2864
	v_add_f32_dpp v174, v174, v174 row_ror:8 row_mask:0xf bank_mask:0xf bound_ctrl:1
	v_pk_mul_f32 v[54:55], v[48:49], v[38:39] op_sel_hi:[0,1]
	v_pk_fma_f32 v[56:57], v[68:69], v[44:45], v[52:53]
	v_add_f32_dpp v174, v174, v174 row_ror:4 row_mask:0xf bank_mask:0xf bound_ctrl:1
	v_pk_fma_f32 v[58:59], v[70:71], v[46:47], v[54:55]
	s_waitcnt vmcnt(12)
	v_add_f32_dpp v174, v174, v174 row_ror:2 row_mask:0xf bank_mask:0xf bound_ctrl:1
	v_lshlrev_b32_e32 v136, 16, v120
	v_and_b32_e32 v137, 0xffff0000, v120
	v_add_f32_dpp v174, v174, v174 row_ror:1 row_mask:0xf bank_mask:0xf bound_ctrl:1
	v_add_f32_dpp v230, v180, v180 row_mirror row_mask:0xf bank_mask:0xf bound_ctrl:1
	v_add_f32_dpp v230, v188, v188 row_mirror row_mask:0xf bank_mask:0xc bound_ctrl:1
	v_pk_fma_f32 v[68:69], v[174:175], v[32:33], v[56:57] op_sel_hi:[0,1,1] neg_lo:[1,0,0] neg_hi:[1,0,0]
	v_pk_fma_f32 v[70:71], v[174:175], v[34:35], v[58:59] op_sel_hi:[0,1,1] neg_lo:[1,0,0] neg_hi:[1,0,0]
	s_waitcnt lgkmcnt(0)
	ds_read_b128 v[28:31], v156 offset:4224
	ds_read_b128 v[36:39], v156 offset:4256
	ds_read_u16_d16_hi v48, v157 offset:4224
	ds_read_b128 v[44:47], v156 offset:4288
	ds_read_b128 v[32:35], v156 offset:4240
	v_pk_mul_f32 v[172:173], v[68:69], v[4:5]
	v_pk_mul_f32 v[178:179], v[68:69], v[40:41]
	v_pk_fma_f32 v[172:173], v[70:71], v[6:7], v[172:173]
	v_pk_fma_f32 v[178:179], v[70:71], v[42:43], v[178:179]
	v_add_f32_e32 v172, v172, v173
	v_add_f32_e32 v197, v178, v179
	v_pk_mul_f32 v[52:53], v[24:25], v[12:13] op_sel_hi:[0,1]
	ds_read_b128 v[40:43], v156 offset:4272
	v_add_f32_dpp v172, v172, v172 row_ror:8 row_mask:0xf bank_mask:0xf bound_ctrl:1
	v_pk_mul_f32 v[54:55], v[24:25], v[14:15] op_sel_hi:[0,1]
	v_pk_fma_f32 v[56:57], v[68:69], v[20:21], v[52:53]
	v_add_f32_dpp v172, v172, v172 row_ror:4 row_mask:0xf bank_mask:0xf bound_ctrl:1
	v_pk_fma_f32 v[58:59], v[70:71], v[22:23], v[54:55]
	v_lshlrev_b32_e32 v138, 16, v121
	v_add_f32_dpp v172, v172, v172 row_ror:2 row_mask:0xf bank_mask:0xf bound_ctrl:1
	v_and_b32_e32 v139, 0xffff0000, v121
	v_lshlrev_b32_e32 v140, 16, v122
	v_add_f32_dpp v172, v172, v172 row_ror:1 row_mask:0xf bank_mask:0xf bound_ctrl:1
	v_add_f32_dpp v231, v181, v181 row_mirror row_mask:0xf bank_mask:0xf bound_ctrl:1
	v_add_f32_dpp v231, v189, v189 row_mirror row_mask:0xf bank_mask:0xc bound_ctrl:1
	v_pk_fma_f32 v[68:69], v[172:173], v[8:9], v[56:57] op_sel_hi:[0,1,1] neg_lo:[1,0,0] neg_hi:[1,0,0]
	v_pk_fma_f32 v[70:71], v[172:173], v[10:11], v[58:59] op_sel_hi:[0,1,1] neg_lo:[1,0,0] neg_hi:[1,0,0]
	s_waitcnt lgkmcnt(0)
	ds_read_b128 v[4:7], v156 offset:5632
	ds_read_b128 v[12:15], v156 offset:5664
	ds_read_u16_d16_hi v24, v157 offset:5632
	ds_read_b128 v[20:23], v156 offset:5696
	ds_read_b128 v[8:11], v156 offset:5648
	v_pk_mul_f32 v[174:175], v[68:69], v[28:29]
	v_pk_mul_f32 v[176:177], v[68:69], v[16:17]
	v_pk_fma_f32 v[174:175], v[70:71], v[30:31], v[174:175]
	v_pk_fma_f32 v[176:177], v[70:71], v[18:19], v[176:177]
	v_add_f32_e32 v174, v174, v175
	v_add_f32_e32 v198, v176, v177
	v_pk_mul_f32 v[52:53], v[48:49], v[36:37] op_sel_hi:[0,1]
	ds_read_b128 v[16:19], v156 offset:5680
	v_add_f32_dpp v174, v174, v174 row_ror:8 row_mask:0xf bank_mask:0xf bound_ctrl:1
	v_pk_mul_f32 v[54:55], v[48:49], v[38:39] op_sel_hi:[0,1]
	v_pk_fma_f32 v[56:57], v[68:69], v[44:45], v[52:53]
	v_add_f32_dpp v174, v174, v174 row_ror:4 row_mask:0xf bank_mask:0xf bound_ctrl:1
	v_pk_fma_f32 v[58:59], v[70:71], v[46:47], v[54:55]
	v_and_b32_e32 v141, 0xffff0000, v122
	v_add_f32_dpp v174, v174, v174 row_ror:2 row_mask:0xf bank_mask:0xf bound_ctrl:1
	v_lshlrev_b32_e32 v142, 16, v123
	v_and_b32_e32 v143, 0xffff0000, v123
	v_add_f32_dpp v174, v174, v174 row_ror:1 row_mask:0xf bank_mask:0xf bound_ctrl:1
	v_add_f32_dpp v232, v182, v182 row_mirror row_mask:0xf bank_mask:0xf bound_ctrl:1
	v_add_f32_dpp v232, v190, v190 row_mirror row_mask:0xf bank_mask:0xc bound_ctrl:1
	v_pk_fma_f32 v[68:69], v[174:175], v[32:33], v[56:57] op_sel_hi:[0,1,1] neg_lo:[1,0,0] neg_hi:[1,0,0]
	v_pk_fma_f32 v[70:71], v[174:175], v[34:35], v[58:59] op_sel_hi:[0,1,1] neg_lo:[1,0,0] neg_hi:[1,0,0]
	s_waitcnt lgkmcnt(0)
	ds_read_b128 v[28:31], v156 offset:7040
	ds_read_b128 v[36:39], v156 offset:7072
	ds_read_u16_d16_hi v48, v157 offset:7040
	ds_read_b128 v[44:47], v156 offset:7104
	ds_read_b128 v[32:35], v156 offset:7056
	v_pk_mul_f32 v[172:173], v[68:69], v[4:5]
	v_pk_mul_f32 v[178:179], v[68:69], v[40:41]
	v_pk_fma_f32 v[172:173], v[70:71], v[6:7], v[172:173]
	v_pk_fma_f32 v[178:179], v[70:71], v[42:43], v[178:179]
	v_add_f32_e32 v172, v172, v173
	v_add_f32_e32 v199, v178, v179
	v_pk_mul_f32 v[52:53], v[24:25], v[12:13] op_sel_hi:[0,1]
	ds_read_b128 v[40:43], v156 offset:7088
	v_add_f32_dpp v172, v172, v172 row_ror:8 row_mask:0xf bank_mask:0xf bound_ctrl:1
	v_pk_mul_f32 v[54:55], v[24:25], v[14:15] op_sel_hi:[0,1]
	v_pk_fma_f32 v[56:57], v[68:69], v[20:21], v[52:53]
	v_add_f32_dpp v172, v172, v172 row_ror:4 row_mask:0xf bank_mask:0xf bound_ctrl:1
	v_pk_fma_f32 v[58:59], v[70:71], v[22:23], v[54:55]
	ds_write_b128 v155, v[136:139] offset:0
	v_add_f32_dpp v172, v172, v172 row_ror:2 row_mask:0xf bank_mask:0xf bound_ctrl:1
	ds_write_b128 v155, v[140:143] offset:80
	v_lshlrev_b32_e32 v136, 16, v124
	v_add_f32_dpp v172, v172, v172 row_ror:1 row_mask:0xf bank_mask:0xf bound_ctrl:1
	v_add_f32_dpp v233, v183, v183 row_mirror row_mask:0xf bank_mask:0xf bound_ctrl:1
	v_add_f32_dpp v233, v191, v191 row_mirror row_mask:0xf bank_mask:0xc bound_ctrl:1
	v_pk_fma_f32 v[68:69], v[172:173], v[8:9], v[56:57] op_sel_hi:[0,1,1] neg_lo:[1,0,0] neg_hi:[1,0,0]
	v_pk_fma_f32 v[70:71], v[172:173], v[10:11], v[58:59] op_sel_hi:[0,1,1] neg_lo:[1,0,0] neg_hi:[1,0,0]
	v_add_f32_dpp v234, v184, v184 row_mirror row_mask:0xf bank_mask:0xf bound_ctrl:1
	s_waitcnt lgkmcnt(2)
	ds_read_b128 v[4:7], v156 offset:8448
	ds_read_b128 v[12:15], v156 offset:8480
	ds_read_u16_d16_hi v24, v157 offset:8448
	ds_read_b128 v[20:23], v156 offset:8512
	ds_read_b128 v[8:11], v156 offset:8464
	v_pk_mul_f32 v[174:175], v[68:69], v[28:29]
	v_pk_mul_f32 v[176:177], v[68:69], v[16:17]
	v_pk_fma_f32 v[174:175], v[70:71], v[30:31], v[174:175]
	v_pk_fma_f32 v[176:177], v[70:71], v[18:19], v[176:177]
	v_add_f32_e32 v174, v174, v175
	v_add_f32_e32 v200, v176, v177
	v_pk_mul_f32 v[52:53], v[48:49], v[36:37] op_sel_hi:[0,1]
	ds_read_b128 v[16:19], v156 offset:8496
	v_add_f32_dpp v174, v174, v174 row_ror:8 row_mask:0xf bank_mask:0xf bound_ctrl:1
	v_pk_mul_f32 v[54:55], v[48:49], v[38:39] op_sel_hi:[0,1]
	v_pk_fma_f32 v[56:57], v[68:69], v[44:45], v[52:53]
	v_add_f32_dpp v174, v174, v174 row_ror:4 row_mask:0xf bank_mask:0xf bound_ctrl:1
	v_pk_fma_f32 v[58:59], v[70:71], v[46:47], v[54:55]
	v_and_b32_e32 v137, 0xffff0000, v124
	v_add_f32_dpp v174, v174, v174 row_ror:2 row_mask:0xf bank_mask:0xf bound_ctrl:1
	v_lshlrev_b32_e32 v138, 16, v125
	v_and_b32_e32 v139, 0xffff0000, v125
	v_add_f32_dpp v174, v174, v174 row_ror:1 row_mask:0xf bank_mask:0xf bound_ctrl:1
	v_add_f32_dpp v234, v192, v192 row_mirror row_mask:0xf bank_mask:0xc bound_ctrl:1
	v_add_f32_dpp v235, v185, v185 row_mirror row_mask:0xf bank_mask:0xf bound_ctrl:1
	v_pk_fma_f32 v[68:69], v[174:175], v[32:33], v[56:57] op_sel_hi:[0,1,1] neg_lo:[1,0,0] neg_hi:[1,0,0]
	v_pk_fma_f32 v[70:71], v[174:175], v[34:35], v[58:59] op_sel_hi:[0,1,1] neg_lo:[1,0,0] neg_hi:[1,0,0]
	s_waitcnt lgkmcnt(0)
	ds_read_b128 v[28:31], v156 offset:9856
	ds_read_b128 v[36:39], v156 offset:9888
	ds_read_u16_d16_hi v48, v157 offset:9856
	ds_read_b128 v[44:47], v156 offset:9920
	ds_read_b128 v[32:35], v156 offset:9872
	v_pk_mul_f32 v[172:173], v[68:69], v[4:5]
	v_pk_mul_f32 v[178:179], v[68:69], v[40:41]
	v_pk_fma_f32 v[172:173], v[70:71], v[6:7], v[172:173]
	v_pk_fma_f32 v[178:179], v[70:71], v[42:43], v[178:179]
	v_add_f32_e32 v172, v172, v173
	v_add_f32_e32 v201, v178, v179
	v_pk_mul_f32 v[52:53], v[24:25], v[12:13] op_sel_hi:[0,1]
	ds_read_b128 v[40:43], v156 offset:9904
	v_add_f32_dpp v172, v172, v172 row_ror:8 row_mask:0xf bank_mask:0xf bound_ctrl:1
	v_pk_mul_f32 v[54:55], v[24:25], v[14:15] op_sel_hi:[0,1]
	v_pk_fma_f32 v[56:57], v[68:69], v[20:21], v[52:53]
	v_add_f32_dpp v172, v172, v172 row_ror:4 row_mask:0xf bank_mask:0xf bound_ctrl:1
	v_pk_fma_f32 v[58:59], v[70:71], v[22:23], v[54:55]
	v_lshlrev_b32_e32 v140, 16, v126
	v_add_f32_dpp v172, v172, v172 row_ror:2 row_mask:0xf bank_mask:0xf bound_ctrl:1
	v_and_b32_e32 v141, 0xffff0000, v126
	v_lshlrev_b32_e32 v142, 16, v127
	v_add_f32_dpp v172, v172, v172 row_ror:1 row_mask:0xf bank_mask:0xf bound_ctrl:1
	v_add_f32_dpp v235, v193, v193 row_mirror row_mask:0xf bank_mask:0xc bound_ctrl:1
	v_add_f32_dpp v236, v186, v186 row_mirror row_mask:0xf bank_mask:0xf bound_ctrl:1
	v_pk_fma_f32 v[68:69], v[172:173], v[8:9], v[56:57] op_sel_hi:[0,1,1] neg_lo:[1,0,0] neg_hi:[1,0,0]
	v_pk_fma_f32 v[70:71], v[172:173], v[10:11], v[58:59] op_sel_hi:[0,1,1] neg_lo:[1,0,0] neg_hi:[1,0,0]
	s_waitcnt lgkmcnt(0)
	ds_read_b128 v[4:7], v156 offset:11264
	ds_read_b128 v[12:15], v156 offset:11296
	ds_read_u16_d16_hi v24, v157 offset:11264
	ds_read_b128 v[20:23], v156 offset:11328
	ds_read_b128 v[8:11], v156 offset:11280
	v_pk_mul_f32 v[174:175], v[68:69], v[28:29]
	v_pk_mul_f32 v[176:177], v[68:69], v[16:17]
	v_pk_fma_f32 v[174:175], v[70:71], v[30:31], v[174:175]
	v_pk_fma_f32 v[176:177], v[70:71], v[18:19], v[176:177]
	v_add_f32_e32 v174, v174, v175
	v_add_f32_e32 v210, v176, v177
	v_pk_mul_f32 v[52:53], v[48:49], v[36:37] op_sel_hi:[0,1]
	ds_read_b128 v[16:19], v156 offset:11312
	v_add_f32_dpp v174, v174, v174 row_ror:8 row_mask:0xf bank_mask:0xf bound_ctrl:1
	v_pk_mul_f32 v[54:55], v[48:49], v[38:39] op_sel_hi:[0,1]
	v_pk_fma_f32 v[56:57], v[68:69], v[44:45], v[52:53]
	v_add_f32_dpp v174, v174, v174 row_ror:4 row_mask:0xf bank_mask:0xf bound_ctrl:1
	v_pk_fma_f32 v[58:59], v[70:71], v[46:47], v[54:55]
	v_and_b32_e32 v143, 0xffff0000, v127
	v_add_f32_dpp v174, v174, v174 row_ror:2 row_mask:0xf bank_mask:0xf bound_ctrl:1
	ds_write_b128 v155, v[136:139] offset:11264
	ds_write_b128 v155, v[140:143] offset:11344
	v_add_f32_dpp v174, v174, v174 row_ror:1 row_mask:0xf bank_mask:0xf bound_ctrl:1
	v_add_f32_dpp v236, v194, v194 row_mirror row_mask:0xf bank_mask:0xc bound_ctrl:1
	v_add_f32_dpp v237, v187, v187 row_mirror row_mask:0xf bank_mask:0xf bound_ctrl:1
	v_pk_fma_f32 v[68:69], v[174:175], v[32:33], v[56:57] op_sel_hi:[0,1,1] neg_lo:[1,0,0] neg_hi:[1,0,0]
	v_pk_fma_f32 v[70:71], v[174:175], v[34:35], v[58:59] op_sel_hi:[0,1,1] neg_lo:[1,0,0] neg_hi:[1,0,0]
	s_waitcnt lgkmcnt(2)
	ds_read_b128 v[28:31], v156 offset:12672
	ds_read_b128 v[36:39], v156 offset:12704
	ds_read_u16_d16_hi v48, v157 offset:12672
	ds_read_b128 v[44:47], v156 offset:12736
	ds_read_b128 v[32:35], v156 offset:12688
	v_pk_mul_f32 v[172:173], v[68:69], v[4:5]
	v_pk_mul_f32 v[178:179], v[68:69], v[40:41]
	v_pk_fma_f32 v[172:173], v[70:71], v[6:7], v[172:173]
	v_pk_fma_f32 v[178:179], v[70:71], v[42:43], v[178:179]
	v_add_f32_e32 v172, v172, v173
	v_add_f32_e32 v211, v178, v179
	v_pk_mul_f32 v[52:53], v[24:25], v[12:13] op_sel_hi:[0,1]
	ds_read_b128 v[40:43], v156 offset:12720
	v_add_f32_dpp v172, v172, v172 row_ror:8 row_mask:0xf bank_mask:0xf bound_ctrl:1
	v_pk_mul_f32 v[54:55], v[24:25], v[14:15] op_sel_hi:[0,1]
	v_pk_fma_f32 v[56:57], v[68:69], v[20:21], v[52:53]
	v_add_f32_dpp v172, v172, v172 row_ror:4 row_mask:0xf bank_mask:0xf bound_ctrl:1
	v_pk_fma_f32 v[58:59], v[70:71], v[22:23], v[54:55]
	ds_write_b128 v165, v[128:131]
	v_add_f32_dpp v172, v172, v172 row_ror:2 row_mask:0xf bank_mask:0xf bound_ctrl:1
	ds_write_b128 v166, v[132:135]
	global_load_dwordx4 v[120:123], v[144:145], off
	v_add_f32_dpp v172, v172, v172 row_ror:1 row_mask:0xf bank_mask:0xf bound_ctrl:1
	v_add_f32_dpp v237, v195, v195 row_mirror row_mask:0xf bank_mask:0xc bound_ctrl:1
	v_add_f32_dpp v238, v230, v230 row_half_mirror row_mask:0xf bank_mask:0xf bound_ctrl:1
	v_pk_fma_f32 v[68:69], v[172:173], v[8:9], v[56:57] op_sel_hi:[0,1,1] neg_lo:[1,0,0] neg_hi:[1,0,0]
	v_pk_fma_f32 v[70:71], v[172:173], v[10:11], v[58:59] op_sel_hi:[0,1,1] neg_lo:[1,0,0] neg_hi:[1,0,0]
	v_add_f32_dpp v238, v234, v234 row_half_mirror row_mask:0xf bank_mask:0xa bound_ctrl:1
	s_waitcnt lgkmcnt(2)
; DEVI void rw_chain_task(const Params& p, int l, int seq, int head, int quarter, char* smem) {
;     ...
;     for (int c = 0; c < nch; c += 4) {
;       lds_barrier();
;       RW_STORE(R1, B1);
;       RW_LOAD(R1, c + 5);
;       RW_COMPUTE(B0, c);
;       lds_barrier();
;       RW_STORE(R2, B0);
;       RW_LOAD(R2, c + 6);
;       RW_COMPUTE(B1, c + 1);
;       lds_barrier();
;       RW_STORE(R3, B1);
;       RW_LOAD(R3, c + 7);
;       RW_COMPUTE(B0, c + 2);
;       lds_barrier();
;       RW_STORE(R0, B0);
;       RW_LOAD(R0, c + 8);
;       RW_COMPUTE(B1, c + 3);
;     }
	ds_read_b128 v[4:7], v156 offset:14080
	ds_read_b128 v[12:15], v156 offset:14112
	ds_read_u16_d16_hi v24, v157 offset:14080
	ds_read_b128 v[20:23], v156 offset:14144
	ds_read_b128 v[8:11], v156 offset:14096
	v_pk_mul_f32 v[174:175], v[68:69], v[28:29]
	v_pk_mul_f32 v[176:177], v[68:69], v[16:17]
	v_pk_fma_f32 v[174:175], v[70:71], v[30:31], v[174:175]
	v_pk_fma_f32 v[176:177], v[70:71], v[18:19], v[176:177]
	v_add_f32_e32 v174, v174, v175
	v_add_f32_e32 v212, v176, v177
	v_pk_mul_f32 v[52:53], v[48:49], v[36:37] op_sel_hi:[0,1]
	ds_read_b128 v[16:19], v156 offset:14128
	v_add_f32_dpp v174, v174, v174 row_ror:8 row_mask:0xf bank_mask:0xf bound_ctrl:1
	v_pk_mul_f32 v[54:55], v[48:49], v[38:39] op_sel_hi:[0,1]
	v_pk_fma_f32 v[56:57], v[68:69], v[44:45], v[52:53]
	v_add_f32_dpp v174, v174, v174 row_ror:4 row_mask:0xf bank_mask:0xf bound_ctrl:1
	v_pk_fma_f32 v[58:59], v[70:71], v[46:47], v[54:55]
	global_load_dwordx4 v[124:127], v[146:147], off
	v_add_f32_dpp v174, v174, v174 row_ror:2 row_mask:0xf bank_mask:0xf bound_ctrl:1
	global_load_dwordx4 v[128:131], v[148:149], off
	global_load_dwordx4 v[132:135], v[150:151], off
	v_add_f32_dpp v174, v174, v174 row_ror:1 row_mask:0xf bank_mask:0xf bound_ctrl:1
	v_add_f32_dpp v239, v231, v231 row_half_mirror row_mask:0xf bank_mask:0xf bound_ctrl:1
	v_add_f32_dpp v239, v235, v235 row_half_mirror row_mask:0xf bank_mask:0xa bound_ctrl:1
	v_pk_fma_f32 v[68:69], v[174:175], v[32:33], v[56:57] op_sel_hi:[0,1,1] neg_lo:[1,0,0] neg_hi:[1,0,0]
	v_pk_fma_f32 v[70:71], v[174:175], v[34:35], v[58:59] op_sel_hi:[0,1,1] neg_lo:[1,0,0] neg_hi:[1,0,0]
	s_waitcnt lgkmcnt(0)
	ds_read_b128 v[28:31], v156 offset:15488
	ds_read_b128 v[36:39], v156 offset:15520
	ds_read_u16_d16_hi v48, v157 offset:15488
	ds_read_b128 v[44:47], v156 offset:15552
	ds_read_b128 v[32:35], v156 offset:15504
	v_pk_mul_f32 v[172:173], v[68:69], v[4:5]
	v_pk_mul_f32 v[178:179], v[68:69], v[40:41]
	v_pk_fma_f32 v[172:173], v[70:71], v[6:7], v[172:173]
	v_pk_fma_f32 v[178:179], v[70:71], v[42:43], v[178:179]
	v_add_f32_e32 v172, v172, v173
	v_add_f32_e32 v213, v178, v179
	v_pk_mul_f32 v[52:53], v[24:25], v[12:13] op_sel_hi:[0,1]
	ds_read_b128 v[40:43], v156 offset:15536
	v_add_f32_dpp v172, v172, v172 row_ror:8 row_mask:0xf bank_mask:0xf bound_ctrl:1
	v_pk_mul_f32 v[54:55], v[24:25], v[14:15] op_sel_hi:[0,1]
	v_pk_fma_f32 v[56:57], v[68:69], v[20:21], v[52:53]
	v_add_f32_dpp v172, v172, v172 row_ror:4 row_mask:0xf bank_mask:0xf bound_ctrl:1
	v_pk_fma_f32 v[58:59], v[70:71], v[22:23], v[54:55]
	v_lshl_add_u64 v[144:145], v[144:145], 0, v[152:153]
	v_add_f32_dpp v172, v172, v172 row_ror:2 row_mask:0xf bank_mask:0xf bound_ctrl:1
	v_lshl_add_u64 v[146:147], v[146:147], 0, v[152:153]
	v_lshl_add_u64 v[148:149], v[148:149], 0, v[62:63]
	v_add_f32_dpp v172, v172, v172 row_ror:1 row_mask:0xf bank_mask:0xf bound_ctrl:1
	v_add_f32_dpp v240, v232, v232 row_half_mirror row_mask:0xf bank_mask:0xf bound_ctrl:1
	v_add_f32_dpp v240, v236, v236 row_half_mirror row_mask:0xf bank_mask:0xa bound_ctrl:1
	v_pk_fma_f32 v[68:69], v[172:173], v[8:9], v[56:57] op_sel_hi:[0,1,1] neg_lo:[1,0,0] neg_hi:[1,0,0]
	v_pk_fma_f32 v[70:71], v[172:173], v[10:11], v[58:59] op_sel_hi:[0,1,1] neg_lo:[1,0,0] neg_hi:[1,0,0]
	s_waitcnt lgkmcnt(0)
	ds_read_b128 v[4:7], v156 offset:16896
	ds_read_b128 v[12:15], v156 offset:16928
	ds_read_u16_d16_hi v24, v157 offset:16896
	ds_read_b128 v[20:23], v156 offset:16960
	ds_read_b128 v[8:11], v156 offset:16912
	v_pk_mul_f32 v[174:175], v[68:69], v[28:29]
	v_pk_mul_f32 v[176:177], v[68:69], v[16:17]
	v_pk_fma_f32 v[174:175], v[70:71], v[30:31], v[174:175]
	v_pk_fma_f32 v[176:177], v[70:71], v[18:19], v[176:177]
	v_add_f32_e32 v174, v174, v175
	v_add_f32_e32 v220, v176, v177
	v_pk_mul_f32 v[52:53], v[48:49], v[36:37] op_sel_hi:[0,1]
	ds_read_b128 v[16:19], v156 offset:16944
	v_add_f32_dpp v174, v174, v174 row_ror:8 row_mask:0xf bank_mask:0xf bound_ctrl:1
	v_pk_mul_f32 v[54:55], v[48:49], v[38:39] op_sel_hi:[0,1]
	v_pk_fma_f32 v[56:57], v[68:69], v[44:45], v[52:53]
	v_add_f32_dpp v174, v174, v174 row_ror:4 row_mask:0xf bank_mask:0xf bound_ctrl:1
	v_pk_fma_f32 v[58:59], v[70:71], v[46:47], v[54:55]
	v_lshl_add_u64 v[150:151], v[150:151], 0, v[64:65]
	v_add_f32_dpp v174, v174, v174 row_ror:2 row_mask:0xf bank_mask:0xf bound_ctrl:1
	v_add_u32_e32 v158, s43, v162
	v_add_u32_e32 v159, s43, v163
	v_add_f32_dpp v174, v174, v174 row_ror:1 row_mask:0xf bank_mask:0xf bound_ctrl:1
	v_add_f32_dpp v241, v233, v233 row_half_mirror row_mask:0xf bank_mask:0xf bound_ctrl:1
	v_add_f32_dpp v241, v237, v237 row_half_mirror row_mask:0xf bank_mask:0xa bound_ctrl:1
	v_pk_fma_f32 v[68:69], v[174:175], v[32:33], v[56:57] op_sel_hi:[0,1,1] neg_lo:[1,0,0] neg_hi:[1,0,0]
	v_pk_fma_f32 v[70:71], v[174:175], v[34:35], v[58:59] op_sel_hi:[0,1,1] neg_lo:[1,0,0] neg_hi:[1,0,0]
	s_waitcnt lgkmcnt(0)
	ds_read_b128 v[28:31], v156 offset:18304
	ds_read_b128 v[36:39], v156 offset:18336
	ds_read_u16_d16_hi v48, v157 offset:18304
	ds_read_b128 v[44:47], v156 offset:18368
	ds_read_b128 v[32:35], v156 offset:18320
	v_pk_mul_f32 v[172:173], v[68:69], v[4:5]
	v_pk_mul_f32 v[178:179], v[68:69], v[40:41]
	v_pk_fma_f32 v[172:173], v[70:71], v[6:7], v[172:173]
	v_pk_fma_f32 v[178:179], v[70:71], v[42:43], v[178:179]
	v_add_f32_e32 v172, v172, v173
	v_add_f32_e32 v221, v178, v179
	v_pk_mul_f32 v[52:53], v[24:25], v[12:13] op_sel_hi:[0,1]
	ds_read_b128 v[40:43], v156 offset:18352
	v_add_f32_dpp v172, v172, v172 row_ror:8 row_mask:0xf bank_mask:0xf bound_ctrl:1
	v_pk_mul_f32 v[54:55], v[24:25], v[14:15] op_sel_hi:[0,1]
	v_pk_fma_f32 v[56:57], v[68:69], v[20:21], v[52:53]
	v_add_f32_dpp v172, v172, v172 row_ror:4 row_mask:0xf bank_mask:0xf bound_ctrl:1
	v_pk_fma_f32 v[58:59], v[70:71], v[22:23], v[54:55]
	v_add_f32_dpp v242, v238, v238 quad_perm:[3,2,1,0] row_mask:0xf bank_mask:0xf bound_ctrl:1
	v_add_f32_dpp v172, v172, v172 row_ror:2 row_mask:0xf bank_mask:0xf bound_ctrl:1
	v_add_f32_dpp v243, v240, v240 quad_perm:[3,2,1,0] row_mask:0xf bank_mask:0xf bound_ctrl:1
	v_cndmask_b32_e64 v244, v242, v243, s[4:5]
	v_add_f32_dpp v172, v172, v172 row_ror:1 row_mask:0xf bank_mask:0xf bound_ctrl:1
	v_pk_fma_f32 v[68:69], v[172:173], v[8:9], v[56:57] op_sel_hi:[0,1,1] neg_lo:[1,0,0] neg_hi:[1,0,0]
	v_pk_fma_f32 v[70:71], v[172:173], v[10:11], v[58:59] op_sel_hi:[0,1,1] neg_lo:[1,0,0] neg_hi:[1,0,0]
	s_waitcnt lgkmcnt(0)
	ds_read_b128 v[4:7], v156 offset:19712
	ds_read_b128 v[12:15], v156 offset:19744
	ds_read_u16_d16_hi v24, v157 offset:19712
	ds_read_b128 v[20:23], v156 offset:19776
	ds_read_b128 v[8:11], v156 offset:19728
	v_pk_mul_f32 v[174:175], v[68:69], v[28:29]
	v_pk_mul_f32 v[176:177], v[68:69], v[16:17]
	v_pk_fma_f32 v[174:175], v[70:71], v[30:31], v[174:175]
	v_pk_fma_f32 v[176:177], v[70:71], v[18:19], v[176:177]
	v_add_f32_e32 v174, v174, v175
	v_add_f32_e32 v222, v176, v177
	v_pk_mul_f32 v[52:53], v[48:49], v[36:37] op_sel_hi:[0,1]
	ds_read_b128 v[16:19], v156 offset:19760
	v_add_f32_dpp v174, v174, v174 row_ror:8 row_mask:0xf bank_mask:0xf bound_ctrl:1
	v_pk_mul_f32 v[54:55], v[48:49], v[38:39] op_sel_hi:[0,1]
	v_pk_fma_f32 v[56:57], v[68:69], v[44:45], v[52:53]
	v_add_f32_dpp v174, v174, v174 row_ror:4 row_mask:0xf bank_mask:0xf bound_ctrl:1
	v_pk_fma_f32 v[58:59], v[70:71], v[46:47], v[54:55]
	v_add_f32_dpp v242, v239, v239 quad_perm:[3,2,1,0] row_mask:0xf bank_mask:0xf bound_ctrl:1
	v_add_f32_dpp v174, v174, v174 row_ror:2 row_mask:0xf bank_mask:0xf bound_ctrl:1
	v_add_f32_dpp v243, v241, v241 quad_perm:[3,2,1,0] row_mask:0xf bank_mask:0xf bound_ctrl:1
	s_nop 0
	v_add_f32_dpp v174, v174, v174 row_ror:1 row_mask:0xf bank_mask:0xf bound_ctrl:1
	v_pk_fma_f32 v[68:69], v[174:175], v[32:33], v[56:57] op_sel_hi:[0,1,1] neg_lo:[1,0,0] neg_hi:[1,0,0]
	v_pk_fma_f32 v[70:71], v[174:175], v[34:35], v[58:59] op_sel_hi:[0,1,1] neg_lo:[1,0,0] neg_hi:[1,0,0]
	s_waitcnt lgkmcnt(0)
	ds_read_b128 v[28:31], v156 offset:21120
	ds_read_b128 v[36:39], v156 offset:21152
	ds_read_u16_d16_hi v48, v157 offset:21120
	ds_read_b128 v[44:47], v156 offset:21184
	ds_read_b128 v[32:35], v156 offset:21136
	v_pk_mul_f32 v[172:173], v[68:69], v[4:5]
	v_pk_mul_f32 v[178:179], v[68:69], v[40:41]
	v_pk_fma_f32 v[172:173], v[70:71], v[6:7], v[172:173]
	v_pk_fma_f32 v[178:179], v[70:71], v[42:43], v[178:179]
	v_add_f32_e32 v172, v172, v173
	v_add_f32_e32 v223, v178, v179
	v_pk_mul_f32 v[52:53], v[24:25], v[12:13] op_sel_hi:[0,1]
	ds_read_b128 v[40:43], v156 offset:21168
	v_add_f32_dpp v172, v172, v172 row_ror:8 row_mask:0xf bank_mask:0xf bound_ctrl:1
	v_pk_mul_f32 v[54:55], v[24:25], v[14:15] op_sel_hi:[0,1]
	v_pk_fma_f32 v[56:57], v[68:69], v[20:21], v[52:53]
	v_add_f32_dpp v172, v172, v172 row_ror:4 row_mask:0xf bank_mask:0xf bound_ctrl:1
	v_pk_fma_f32 v[58:59], v[70:71], v[22:23], v[54:55]
	v_cndmask_b32_e64 v245, v242, v243, s[4:5]
	v_add_f32_dpp v172, v172, v172 row_ror:2 row_mask:0xf bank_mask:0xf bound_ctrl:1
	v_add_f32_dpp v242, v244, v244 quad_perm:[1,0,3,2] row_mask:0xf bank_mask:0xf bound_ctrl:1
	s_nop 0
	v_add_f32_dpp v172, v172, v172 row_ror:1 row_mask:0xf bank_mask:0xf bound_ctrl:1
	v_pk_fma_f32 v[68:69], v[172:173], v[8:9], v[56:57] op_sel_hi:[0,1,1] neg_lo:[1,0,0] neg_hi:[1,0,0]
	v_pk_fma_f32 v[70:71], v[172:173], v[10:11], v[58:59] op_sel_hi:[0,1,1] neg_lo:[1,0,0] neg_hi:[1,0,0]
	s_waitcnt lgkmcnt(0)
	ds_read_b128 v[4:7], v158 offset:0
	ds_read_b128 v[12:15], v158 offset:32
	ds_read_u16_d16_hi v24, v159 offset:0
	ds_read_b128 v[20:23], v158 offset:64
	ds_read_b128 v[8:11], v158 offset:16
	v_pk_mul_f32 v[174:175], v[68:69], v[28:29]
	v_pk_mul_f32 v[176:177], v[68:69], v[16:17]
	v_pk_fma_f32 v[174:175], v[70:71], v[30:31], v[174:175]
	v_pk_fma_f32 v[176:177], v[70:71], v[18:19], v[176:177]
	v_add_f32_e32 v174, v174, v175
	v_add_f32_e32 v224, v176, v177
	v_pk_mul_f32 v[52:53], v[48:49], v[36:37] op_sel_hi:[0,1]
	ds_read_b128 v[16:19], v158 offset:48
	v_add_f32_dpp v174, v174, v174 row_ror:8 row_mask:0xf bank_mask:0xf bound_ctrl:1
	v_pk_mul_f32 v[54:55], v[48:49], v[38:39] op_sel_hi:[0,1]
	v_pk_fma_f32 v[56:57], v[68:69], v[44:45], v[52:53]
	v_add_f32_dpp v174, v174, v174 row_ror:4 row_mask:0xf bank_mask:0xf bound_ctrl:1
	v_pk_fma_f32 v[58:59], v[70:71], v[46:47], v[54:55]
	v_add_f32_dpp v243, v245, v245 quad_perm:[1,0,3,2] row_mask:0xf bank_mask:0xf bound_ctrl:1
	v_add_f32_dpp v174, v174, v174 row_ror:2 row_mask:0xf bank_mask:0xf bound_ctrl:1
	v_cndmask_b32_e64 v246, v242, v243, s[6:7]
	v_bfe_u32 v61, v246, 16, 1
	v_add3_u32 v61, v246, v61, s33
	global_store_short_d16_hi v[160:161], v61, off
	v_lshl_add_u64 v[160:161], v[160:161], 0, s[46:47]
	v_add_f32_dpp v174, v174, v174 row_ror:1 row_mask:0xf bank_mask:0xf bound_ctrl:1
	v_pk_fma_f32 v[68:69], v[174:175], v[32:33], v[56:57] op_sel_hi:[0,1,1] neg_lo:[1,0,0] neg_hi:[1,0,0]
	v_pk_fma_f32 v[70:71], v[174:175], v[34:35], v[58:59] op_sel_hi:[0,1,1] neg_lo:[1,0,0] neg_hi:[1,0,0]
	s_waitcnt lgkmcnt(0)
	s_barrier
; DEVI void rw_chain_task(const Params& p, int l, int seq, int head, int quarter, char* smem) {
;     ...
;     for (int c = 0; c < nch; c += 4) {
;       lds_barrier();
;       RW_STORE(R1, B1);
;       RW_LOAD(R1, c + 5);
;       RW_COMPUTE(B0, c);
;       lds_barrier();
;       RW_STORE(R2, B0);
;       RW_LOAD(R2, c + 6);
;       RW_COMPUTE(B1, c + 1);
;       lds_barrier();
;       RW_STORE(R3, B1);
;       RW_LOAD(R3, c + 7);
;       RW_COMPUTE(B0, c + 2);
;       lds_barrier();
;       RW_STORE(R0, B0);
;       RW_LOAD(R0, c + 8);
;       RW_COMPUTE(B1, c + 3);
;     }
	s_mov_b32 vcc_lo, s42
	s_mov_b32 s42, s43
	s_mov_b32 s43, s45
	s_mov_b32 s45, vcc_lo
	v_add_u32_e32 v156, s42, v162
	v_add_u32_e32 v157, s42, v163
	v_add_u32_e32 v155, s45, v164
	v_add_u32_e32 v165, s45, v167
	v_add_u32_e32 v166, s45, v168
	s_waitcnt lgkmcnt(0)
	ds_read_b128 v[28:31], v156 offset:1408
	ds_read_b128 v[36:39], v156 offset:1440
	ds_read_u16_d16_hi v48, v157 offset:1408
	ds_read_b128 v[44:47], v156 offset:1472
	ds_read_b128 v[32:35], v156 offset:1424
	v_pk_mul_f32 v[172:173], v[68:69], v[4:5]
	v_pk_mul_f32 v[178:179], v[68:69], v[40:41]
	v_pk_fma_f32 v[172:173], v[70:71], v[6:7], v[172:173]
	v_pk_fma_f32 v[178:179], v[70:71], v[42:43], v[178:179]
	v_add_f32_e32 v172, v172, v173
	v_add_f32_e32 v225, v178, v179
	v_pk_mul_f32 v[52:53], v[24:25], v[12:13] op_sel_hi:[0,1]
	ds_read_b128 v[40:43], v156 offset:1456
	v_add_f32_dpp v172, v172, v172 row_ror:8 row_mask:0xf bank_mask:0xf bound_ctrl:1
	v_pk_mul_f32 v[54:55], v[24:25], v[14:15] op_sel_hi:[0,1]
	v_pk_fma_f32 v[56:57], v[68:69], v[20:21], v[52:53]
	v_add_f32_dpp v172, v172, v172 row_ror:4 row_mask:0xf bank_mask:0xf bound_ctrl:1
	v_pk_fma_f32 v[58:59], v[70:71], v[22:23], v[54:55]
	s_nop 0
	v_add_f32_dpp v172, v172, v172 row_ror:2 row_mask:0xf bank_mask:0xf bound_ctrl:1
	s_nop 1
	v_add_f32_dpp v172, v172, v172 row_ror:1 row_mask:0xf bank_mask:0xf bound_ctrl:1
	v_pk_fma_f32 v[68:69], v[172:173], v[8:9], v[56:57] op_sel_hi:[0,1,1] neg_lo:[1,0,0] neg_hi:[1,0,0]
	v_pk_fma_f32 v[70:71], v[172:173], v[10:11], v[58:59] op_sel_hi:[0,1,1] neg_lo:[1,0,0] neg_hi:[1,0,0]
	s_waitcnt lgkmcnt(0)
	ds_read_b128 v[4:7], v156 offset:2816
	ds_read_b128 v[12:15], v156 offset:2848
	ds_read_u16_d16_hi v24, v157 offset:2816
	ds_read_b128 v[20:23], v156 offset:2880
	ds_read_b128 v[8:11], v156 offset:2832
	v_pk_mul_f32 v[174:175], v[68:69], v[28:29]
	v_pk_mul_f32 v[176:177], v[68:69], v[16:17]
	v_pk_fma_f32 v[174:175], v[70:71], v[30:31], v[174:175]
	v_pk_fma_f32 v[176:177], v[70:71], v[18:19], v[176:177]
	v_add_f32_e32 v174, v174, v175
	v_add_f32_e32 v180, v176, v177
	v_pk_mul_f32 v[52:53], v[48:49], v[36:37] op_sel_hi:[0,1]
	ds_read_b128 v[16:19], v156 offset:2864
	v_add_f32_dpp v174, v174, v174 row_ror:8 row_mask:0xf bank_mask:0xf bound_ctrl:1
	v_pk_mul_f32 v[54:55], v[48:49], v[38:39] op_sel_hi:[0,1]
	v_pk_fma_f32 v[56:57], v[68:69], v[44:45], v[52:53]
	v_add_f32_dpp v174, v174, v174 row_ror:4 row_mask:0xf bank_mask:0xf bound_ctrl:1
	v_pk_fma_f32 v[58:59], v[70:71], v[46:47], v[54:55]
	s_waitcnt vmcnt(12)
	v_add_f32_dpp v174, v174, v174 row_ror:2 row_mask:0xf bank_mask:0xf bound_ctrl:1
	v_lshlrev_b32_e32 v136, 16, v72
	v_and_b32_e32 v137, 0xffff0000, v72
	v_add_f32_dpp v174, v174, v174 row_ror:1 row_mask:0xf bank_mask:0xf bound_ctrl:1
	v_add_f32_dpp v230, v196, v196 row_mirror row_mask:0xf bank_mask:0xf bound_ctrl:1
	v_add_f32_dpp v230, v212, v212 row_mirror row_mask:0xf bank_mask:0xc bound_ctrl:1
	v_pk_fma_f32 v[68:69], v[174:175], v[32:33], v[56:57] op_sel_hi:[0,1,1] neg_lo:[1,0,0] neg_hi:[1,0,0]
	v_pk_fma_f32 v[70:71], v[174:175], v[34:35], v[58:59] op_sel_hi:[0,1,1] neg_lo:[1,0,0] neg_hi:[1,0,0]
	s_waitcnt lgkmcnt(0)
	ds_read_b128 v[28:31], v156 offset:4224
	ds_read_b128 v[36:39], v156 offset:4256
	ds_read_u16_d16_hi v48, v157 offset:4224
	ds_read_b128 v[44:47], v156 offset:4288
	ds_read_b128 v[32:35], v156 offset:4240
	v_pk_mul_f32 v[172:173], v[68:69], v[4:5]
	v_pk_mul_f32 v[178:179], v[68:69], v[40:41]
	v_pk_fma_f32 v[172:173], v[70:71], v[6:7], v[172:173]
	v_pk_fma_f32 v[178:179], v[70:71], v[42:43], v[178:179]
	v_add_f32_e32 v172, v172, v173
	v_add_f32_e32 v181, v178, v179
	v_pk_mul_f32 v[52:53], v[24:25], v[12:13] op_sel_hi:[0,1]
	ds_read_b128 v[40:43], v156 offset:4272
	v_add_f32_dpp v172, v172, v172 row_ror:8 row_mask:0xf bank_mask:0xf bound_ctrl:1
	v_pk_mul_f32 v[54:55], v[24:25], v[14:15] op_sel_hi:[0,1]
	v_pk_fma_f32 v[56:57], v[68:69], v[20:21], v[52:53]
	v_add_f32_dpp v172, v172, v172 row_ror:4 row_mask:0xf bank_mask:0xf bound_ctrl:1
	v_pk_fma_f32 v[58:59], v[70:71], v[22:23], v[54:55]
	v_lshlrev_b32_e32 v138, 16, v73
	v_add_f32_dpp v172, v172, v172 row_ror:2 row_mask:0xf bank_mask:0xf bound_ctrl:1
	v_and_b32_e32 v139, 0xffff0000, v73
	v_lshlrev_b32_e32 v140, 16, v74
	v_add_f32_dpp v172, v172, v172 row_ror:1 row_mask:0xf bank_mask:0xf bound_ctrl:1
	v_add_f32_dpp v231, v197, v197 row_mirror row_mask:0xf bank_mask:0xf bound_ctrl:1
	v_add_f32_dpp v231, v213, v213 row_mirror row_mask:0xf bank_mask:0xc bound_ctrl:1
	v_pk_fma_f32 v[68:69], v[172:173], v[8:9], v[56:57] op_sel_hi:[0,1,1] neg_lo:[1,0,0] neg_hi:[1,0,0]
	v_pk_fma_f32 v[70:71], v[172:173], v[10:11], v[58:59] op_sel_hi:[0,1,1] neg_lo:[1,0,0] neg_hi:[1,0,0]
	s_waitcnt lgkmcnt(0)
	ds_read_b128 v[4:7], v156 offset:5632
	ds_read_b128 v[12:15], v156 offset:5664
	ds_read_u16_d16_hi v24, v157 offset:5632
	ds_read_b128 v[20:23], v156 offset:5696
	ds_read_b128 v[8:11], v156 offset:5648
	v_pk_mul_f32 v[174:175], v[68:69], v[28:29]
	v_pk_mul_f32 v[176:177], v[68:69], v[16:17]
	v_pk_fma_f32 v[174:175], v[70:71], v[30:31], v[174:175]
	v_pk_fma_f32 v[176:177], v[70:71], v[18:19], v[176:177]
	v_add_f32_e32 v174, v174, v175
	v_add_f32_e32 v182, v176, v177
	v_pk_mul_f32 v[52:53], v[48:49], v[36:37] op_sel_hi:[0,1]
	ds_read_b128 v[16:19], v156 offset:5680
	v_add_f32_dpp v174, v174, v174 row_ror:8 row_mask:0xf bank_mask:0xf bound_ctrl:1
	v_pk_mul_f32 v[54:55], v[48:49], v[38:39] op_sel_hi:[0,1]
	v_pk_fma_f32 v[56:57], v[68:69], v[44:45], v[52:53]
	v_add_f32_dpp v174, v174, v174 row_ror:4 row_mask:0xf bank_mask:0xf bound_ctrl:1
	v_pk_fma_f32 v[58:59], v[70:71], v[46:47], v[54:55]
	v_and_b32_e32 v141, 0xffff0000, v74
	v_add_f32_dpp v174, v174, v174 row_ror:2 row_mask:0xf bank_mask:0xf bound_ctrl:1
	v_lshlrev_b32_e32 v142, 16, v75
	v_and_b32_e32 v143, 0xffff0000, v75
	v_add_f32_dpp v174, v174, v174 row_ror:1 row_mask:0xf bank_mask:0xf bound_ctrl:1
	v_add_f32_dpp v232, v198, v198 row_mirror row_mask:0xf bank_mask:0xf bound_ctrl:1
	v_add_f32_dpp v232, v220, v220 row_mirror row_mask:0xf bank_mask:0xc bound_ctrl:1
	v_pk_fma_f32 v[68:69], v[174:175], v[32:33], v[56:57] op_sel_hi:[0,1,1] neg_lo:[1,0,0] neg_hi:[1,0,0]
	v_pk_fma_f32 v[70:71], v[174:175], v[34:35], v[58:59] op_sel_hi:[0,1,1] neg_lo:[1,0,0] neg_hi:[1,0,0]
	s_waitcnt lgkmcnt(0)
; DEVI void rw_chain_task(const Params& p, int l, int seq, int head, int quarter, char* smem) {
;     ...
;     for (int c = 0; c < nch; c += 4) {
;       lds_barrier();
;       RW_STORE(R1, B1);
;       RW_LOAD(R1, c + 5);
;       RW_COMPUTE(B0, c);
;       lds_barrier();
;       RW_STORE(R2, B0);
;       RW_LOAD(R2, c + 6);
;       RW_COMPUTE(B1, c + 1);
;       lds_barrier();
;       RW_STORE(R3, B1);
;       RW_LOAD(R3, c + 7);
;       RW_COMPUTE(B0, c + 2);
;       lds_barrier();
;       RW_STORE(R0, B0);
;       RW_LOAD(R0, c + 8);
;       RW_COMPUTE(B1, c + 3);
;     }
	ds_read_b128 v[28:31], v156 offset:7040
	ds_read_b128 v[36:39], v156 offset:7072
	ds_read_u16_d16_hi v48, v157 offset:7040
	ds_read_b128 v[44:47], v156 offset:7104
	ds_read_b128 v[32:35], v156 offset:7056
	v_pk_mul_f32 v[172:173], v[68:69], v[4:5]
	v_pk_mul_f32 v[178:179], v[68:69], v[40:41]
	v_pk_fma_f32 v[172:173], v[70:71], v[6:7], v[172:173]
	v_pk_fma_f32 v[178:179], v[70:71], v[42:43], v[178:179]
	v_add_f32_e32 v172, v172, v173
	v_add_f32_e32 v183, v178, v179
	v_pk_mul_f32 v[52:53], v[24:25], v[12:13] op_sel_hi:[0,1]
	ds_read_b128 v[40:43], v156 offset:7088
	v_add_f32_dpp v172, v172, v172 row_ror:8 row_mask:0xf bank_mask:0xf bound_ctrl:1
	v_pk_mul_f32 v[54:55], v[24:25], v[14:15] op_sel_hi:[0,1]
	v_pk_fma_f32 v[56:57], v[68:69], v[20:21], v[52:53]
	v_add_f32_dpp v172, v172, v172 row_ror:4 row_mask:0xf bank_mask:0xf bound_ctrl:1
	v_pk_fma_f32 v[58:59], v[70:71], v[22:23], v[54:55]
	ds_write_b128 v155, v[136:139] offset:0
	v_add_f32_dpp v172, v172, v172 row_ror:2 row_mask:0xf bank_mask:0xf bound_ctrl:1
	ds_write_b128 v155, v[140:143] offset:80
	v_lshlrev_b32_e32 v136, 16, v76
	v_add_f32_dpp v172, v172, v172 row_ror:1 row_mask:0xf bank_mask:0xf bound_ctrl:1
	v_add_f32_dpp v233, v199, v199 row_mirror row_mask:0xf bank_mask:0xf bound_ctrl:1
	v_add_f32_dpp v233, v221, v221 row_mirror row_mask:0xf bank_mask:0xc bound_ctrl:1
	v_pk_fma_f32 v[68:69], v[172:173], v[8:9], v[56:57] op_sel_hi:[0,1,1] neg_lo:[1,0,0] neg_hi:[1,0,0]
	v_pk_fma_f32 v[70:71], v[172:173], v[10:11], v[58:59] op_sel_hi:[0,1,1] neg_lo:[1,0,0] neg_hi:[1,0,0]
	v_add_f32_dpp v234, v200, v200 row_mirror row_mask:0xf bank_mask:0xf bound_ctrl:1
	s_waitcnt lgkmcnt(2)
	ds_read_b128 v[4:7], v156 offset:8448
	ds_read_b128 v[12:15], v156 offset:8480
	ds_read_u16_d16_hi v24, v157 offset:8448
	ds_read_b128 v[20:23], v156 offset:8512
	ds_read_b128 v[8:11], v156 offset:8464
	v_pk_mul_f32 v[174:175], v[68:69], v[28:29]
	v_pk_mul_f32 v[176:177], v[68:69], v[16:17]
	v_pk_fma_f32 v[174:175], v[70:71], v[30:31], v[174:175]
	v_pk_fma_f32 v[176:177], v[70:71], v[18:19], v[176:177]
	v_add_f32_e32 v174, v174, v175
	v_add_f32_e32 v184, v176, v177
	v_pk_mul_f32 v[52:53], v[48:49], v[36:37] op_sel_hi:[0,1]
	ds_read_b128 v[16:19], v156 offset:8496
	v_add_f32_dpp v174, v174, v174 row_ror:8 row_mask:0xf bank_mask:0xf bound_ctrl:1
	v_pk_mul_f32 v[54:55], v[48:49], v[38:39] op_sel_hi:[0,1]
	v_pk_fma_f32 v[56:57], v[68:69], v[44:45], v[52:53]
	v_add_f32_dpp v174, v174, v174 row_ror:4 row_mask:0xf bank_mask:0xf bound_ctrl:1
	v_pk_fma_f32 v[58:59], v[70:71], v[46:47], v[54:55]
	v_and_b32_e32 v137, 0xffff0000, v76
	v_add_f32_dpp v174, v174, v174 row_ror:2 row_mask:0xf bank_mask:0xf bound_ctrl:1
	v_lshlrev_b32_e32 v138, 16, v77
	v_and_b32_e32 v139, 0xffff0000, v77
	v_add_f32_dpp v174, v174, v174 row_ror:1 row_mask:0xf bank_mask:0xf bound_ctrl:1
	v_add_f32_dpp v234, v222, v222 row_mirror row_mask:0xf bank_mask:0xc bound_ctrl:1
	v_add_f32_dpp v235, v201, v201 row_mirror row_mask:0xf bank_mask:0xf bound_ctrl:1
	v_pk_fma_f32 v[68:69], v[174:175], v[32:33], v[56:57] op_sel_hi:[0,1,1] neg_lo:[1,0,0] neg_hi:[1,0,0]
	v_pk_fma_f32 v[70:71], v[174:175], v[34:35], v[58:59] op_sel_hi:[0,1,1] neg_lo:[1,0,0] neg_hi:[1,0,0]
	s_waitcnt lgkmcnt(0)
	ds_read_b128 v[28:31], v156 offset:9856
	ds_read_b128 v[36:39], v156 offset:9888
	ds_read_u16_d16_hi v48, v157 offset:9856
	ds_read_b128 v[44:47], v156 offset:9920
	ds_read_b128 v[32:35], v156 offset:9872
	v_pk_mul_f32 v[172:173], v[68:69], v[4:5]
	v_pk_mul_f32 v[178:179], v[68:69], v[40:41]
	v_pk_fma_f32 v[172:173], v[70:71], v[6:7], v[172:173]
	v_pk_fma_f32 v[178:179], v[70:71], v[42:43], v[178:179]
	v_add_f32_e32 v172, v172, v173
	v_add_f32_e32 v185, v178, v179
	v_pk_mul_f32 v[52:53], v[24:25], v[12:13] op_sel_hi:[0,1]
	ds_read_b128 v[40:43], v156 offset:9904
	v_add_f32_dpp v172, v172, v172 row_ror:8 row_mask:0xf bank_mask:0xf bound_ctrl:1
	v_pk_mul_f32 v[54:55], v[24:25], v[14:15] op_sel_hi:[0,1]
	v_pk_fma_f32 v[56:57], v[68:69], v[20:21], v[52:53]
	v_add_f32_dpp v172, v172, v172 row_ror:4 row_mask:0xf bank_mask:0xf bound_ctrl:1
	v_pk_fma_f32 v[58:59], v[70:71], v[22:23], v[54:55]
	v_lshlrev_b32_e32 v140, 16, v78
	v_add_f32_dpp v172, v172, v172 row_ror:2 row_mask:0xf bank_mask:0xf bound_ctrl:1
	v_and_b32_e32 v141, 0xffff0000, v78
	v_lshlrev_b32_e32 v142, 16, v79
	v_add_f32_dpp v172, v172, v172 row_ror:1 row_mask:0xf bank_mask:0xf bound_ctrl:1
	v_add_f32_dpp v235, v223, v223 row_mirror row_mask:0xf bank_mask:0xc bound_ctrl:1
	v_add_f32_dpp v236, v210, v210 row_mirror row_mask:0xf bank_mask:0xf bound_ctrl:1
	v_pk_fma_f32 v[68:69], v[172:173], v[8:9], v[56:57] op_sel_hi:[0,1,1] neg_lo:[1,0,0] neg_hi:[1,0,0]
	v_pk_fma_f32 v[70:71], v[172:173], v[10:11], v[58:59] op_sel_hi:[0,1,1] neg_lo:[1,0,0] neg_hi:[1,0,0]
	s_waitcnt lgkmcnt(0)
	ds_read_b128 v[4:7], v156 offset:11264
	ds_read_b128 v[12:15], v156 offset:11296
	ds_read_u16_d16_hi v24, v157 offset:11264
	ds_read_b128 v[20:23], v156 offset:11328
	ds_read_b128 v[8:11], v156 offset:11280
	v_pk_mul_f32 v[174:175], v[68:69], v[28:29]
	v_pk_mul_f32 v[176:177], v[68:69], v[16:17]
	v_pk_fma_f32 v[174:175], v[70:71], v[30:31], v[174:175]
	v_pk_fma_f32 v[176:177], v[70:71], v[18:19], v[176:177]
	v_add_f32_e32 v174, v174, v175
	v_add_f32_e32 v186, v176, v177
	v_pk_mul_f32 v[52:53], v[48:49], v[36:37] op_sel_hi:[0,1]
	ds_read_b128 v[16:19], v156 offset:11312
	v_add_f32_dpp v174, v174, v174 row_ror:8 row_mask:0xf bank_mask:0xf bound_ctrl:1
	v_pk_mul_f32 v[54:55], v[48:49], v[38:39] op_sel_hi:[0,1]
	v_pk_fma_f32 v[56:57], v[68:69], v[44:45], v[52:53]
	v_add_f32_dpp v174, v174, v174 row_ror:4 row_mask:0xf bank_mask:0xf bound_ctrl:1
	v_pk_fma_f32 v[58:59], v[70:71], v[46:47], v[54:55]
	v_and_b32_e32 v143, 0xffff0000, v79
	v_add_f32_dpp v174, v174, v174 row_ror:2 row_mask:0xf bank_mask:0xf bound_ctrl:1
	ds_write_b128 v155, v[136:139] offset:11264
	ds_write_b128 v155, v[140:143] offset:11344
	v_add_f32_dpp v174, v174, v174 row_ror:1 row_mask:0xf bank_mask:0xf bound_ctrl:1
	v_add_f32_dpp v236, v224, v224 row_mirror row_mask:0xf bank_mask:0xc bound_ctrl:1
	v_add_f32_dpp v237, v211, v211 row_mirror row_mask:0xf bank_mask:0xf bound_ctrl:1
	v_pk_fma_f32 v[68:69], v[174:175], v[32:33], v[56:57] op_sel_hi:[0,1,1] neg_lo:[1,0,0] neg_hi:[1,0,0]
	v_pk_fma_f32 v[70:71], v[174:175], v[34:35], v[58:59] op_sel_hi:[0,1,1] neg_lo:[1,0,0] neg_hi:[1,0,0]
	s_waitcnt lgkmcnt(2)
; DEVI void rw_chain_task(const Params& p, int l, int seq, int head, int quarter, char* smem) {
;     ...
;     for (int c = 0; c < nch; c += 4) {
;       lds_barrier();
;       RW_STORE(R1, B1);
;       RW_LOAD(R1, c + 5);
;       RW_COMPUTE(B0, c);
;       lds_barrier();
;       RW_STORE(R2, B0);
;       RW_LOAD(R2, c + 6);
;       RW_COMPUTE(B1, c + 1);
;       lds_barrier();
;       RW_STORE(R3, B1);
;       RW_LOAD(R3, c + 7);
;       RW_COMPUTE(B0, c + 2);
;       lds_barrier();
;       RW_STORE(R0, B0);
;       RW_LOAD(R0, c + 8);
;       RW_COMPUTE(B1, c + 3);
;     }
	ds_read_b128 v[28:31], v156 offset:12672
	ds_read_b128 v[36:39], v156 offset:12704
	ds_read_u16_d16_hi v48, v157 offset:12672
	ds_read_b128 v[44:47], v156 offset:12736
	ds_read_b128 v[32:35], v156 offset:12688
	v_pk_mul_f32 v[172:173], v[68:69], v[4:5]
	v_pk_mul_f32 v[178:179], v[68:69], v[40:41]
	v_pk_fma_f32 v[172:173], v[70:71], v[6:7], v[172:173]
	v_pk_fma_f32 v[178:179], v[70:71], v[42:43], v[178:179]
	v_add_f32_e32 v172, v172, v173
	v_add_f32_e32 v187, v178, v179
	v_pk_mul_f32 v[52:53], v[24:25], v[12:13] op_sel_hi:[0,1]
	ds_read_b128 v[40:43], v156 offset:12720
	v_add_f32_dpp v172, v172, v172 row_ror:8 row_mask:0xf bank_mask:0xf bound_ctrl:1
	v_pk_mul_f32 v[54:55], v[24:25], v[14:15] op_sel_hi:[0,1]
	v_pk_fma_f32 v[56:57], v[68:69], v[20:21], v[52:53]
	v_add_f32_dpp v172, v172, v172 row_ror:4 row_mask:0xf bank_mask:0xf bound_ctrl:1
	v_pk_fma_f32 v[58:59], v[70:71], v[22:23], v[54:55]
	ds_write_b128 v165, v[80:83]
	v_add_f32_dpp v172, v172, v172 row_ror:2 row_mask:0xf bank_mask:0xf bound_ctrl:1
	ds_write_b128 v166, v[84:87]
	global_load_dwordx4 v[72:75], v[144:145], off
	v_add_f32_dpp v172, v172, v172 row_ror:1 row_mask:0xf bank_mask:0xf bound_ctrl:1
	v_add_f32_dpp v237, v225, v225 row_mirror row_mask:0xf bank_mask:0xc bound_ctrl:1
	v_add_f32_dpp v238, v230, v230 row_half_mirror row_mask:0xf bank_mask:0xf bound_ctrl:1
	v_pk_fma_f32 v[68:69], v[172:173], v[8:9], v[56:57] op_sel_hi:[0,1,1] neg_lo:[1,0,0] neg_hi:[1,0,0]
	v_pk_fma_f32 v[70:71], v[172:173], v[10:11], v[58:59] op_sel_hi:[0,1,1] neg_lo:[1,0,0] neg_hi:[1,0,0]
	v_add_f32_dpp v238, v234, v234 row_half_mirror row_mask:0xf bank_mask:0xa bound_ctrl:1
	s_waitcnt lgkmcnt(2)
	ds_read_b128 v[4:7], v156 offset:14080
	ds_read_b128 v[12:15], v156 offset:14112
	ds_read_u16_d16_hi v24, v157 offset:14080
	ds_read_b128 v[20:23], v156 offset:14144
	ds_read_b128 v[8:11], v156 offset:14096
	v_pk_mul_f32 v[174:175], v[68:69], v[28:29]
	v_pk_mul_f32 v[176:177], v[68:69], v[16:17]
	v_pk_fma_f32 v[174:175], v[70:71], v[30:31], v[174:175]
	v_pk_fma_f32 v[176:177], v[70:71], v[18:19], v[176:177]
	v_add_f32_e32 v174, v174, v175
	v_add_f32_e32 v188, v176, v177
	v_pk_mul_f32 v[52:53], v[48:49], v[36:37] op_sel_hi:[0,1]
	ds_read_b128 v[16:19], v156 offset:14128
	v_add_f32_dpp v174, v174, v174 row_ror:8 row_mask:0xf bank_mask:0xf bound_ctrl:1
	v_pk_mul_f32 v[54:55], v[48:49], v[38:39] op_sel_hi:[0,1]
	v_pk_fma_f32 v[56:57], v[68:69], v[44:45], v[52:53]
	v_add_f32_dpp v174, v174, v174 row_ror:4 row_mask:0xf bank_mask:0xf bound_ctrl:1
	v_pk_fma_f32 v[58:59], v[70:71], v[46:47], v[54:55]
	global_load_dwordx4 v[76:79], v[146:147], off
	v_add_f32_dpp v174, v174, v174 row_ror:2 row_mask:0xf bank_mask:0xf bound_ctrl:1
	global_load_dwordx4 v[80:83], v[148:149], off
	global_load_dwordx4 v[84:87], v[150:151], off
	v_add_f32_dpp v174, v174, v174 row_ror:1 row_mask:0xf bank_mask:0xf bound_ctrl:1
	v_add_f32_dpp v239, v231, v231 row_half_mirror row_mask:0xf bank_mask:0xf bound_ctrl:1
	v_add_f32_dpp v239, v235, v235 row_half_mirror row_mask:0xf bank_mask:0xa bound_ctrl:1
	v_pk_fma_f32 v[68:69], v[174:175], v[32:33], v[56:57] op_sel_hi:[0,1,1] neg_lo:[1,0,0] neg_hi:[1,0,0]
	v_pk_fma_f32 v[70:71], v[174:175], v[34:35], v[58:59] op_sel_hi:[0,1,1] neg_lo:[1,0,0] neg_hi:[1,0,0]
	s_waitcnt lgkmcnt(0)
	ds_read_b128 v[28:31], v156 offset:15488
	ds_read_b128 v[36:39], v156 offset:15520
	ds_read_u16_d16_hi v48, v157 offset:15488
	ds_read_b128 v[44:47], v156 offset:15552
	ds_read_b128 v[32:35], v156 offset:15504
	v_pk_mul_f32 v[172:173], v[68:69], v[4:5]
	v_pk_mul_f32 v[178:179], v[68:69], v[40:41]
	v_pk_fma_f32 v[172:173], v[70:71], v[6:7], v[172:173]
	v_pk_fma_f32 v[178:179], v[70:71], v[42:43], v[178:179]
	v_add_f32_e32 v172, v172, v173
	v_add_f32_e32 v189, v178, v179
	v_pk_mul_f32 v[52:53], v[24:25], v[12:13] op_sel_hi:[0,1]
	ds_read_b128 v[40:43], v156 offset:15536
	v_add_f32_dpp v172, v172, v172 row_ror:8 row_mask:0xf bank_mask:0xf bound_ctrl:1
	v_pk_mul_f32 v[54:55], v[24:25], v[14:15] op_sel_hi:[0,1]
	v_pk_fma_f32 v[56:57], v[68:69], v[20:21], v[52:53]
	v_add_f32_dpp v172, v172, v172 row_ror:4 row_mask:0xf bank_mask:0xf bound_ctrl:1
	v_pk_fma_f32 v[58:59], v[70:71], v[22:23], v[54:55]
	v_lshl_add_u64 v[144:145], v[144:145], 0, v[152:153]
	v_add_f32_dpp v172, v172, v172 row_ror:2 row_mask:0xf bank_mask:0xf bound_ctrl:1
	v_lshl_add_u64 v[146:147], v[146:147], 0, v[152:153]
	v_lshl_add_u64 v[148:149], v[148:149], 0, v[62:63]
	v_add_f32_dpp v172, v172, v172 row_ror:1 row_mask:0xf bank_mask:0xf bound_ctrl:1
	v_add_f32_dpp v240, v232, v232 row_half_mirror row_mask:0xf bank_mask:0xf bound_ctrl:1
	v_add_f32_dpp v240, v236, v236 row_half_mirror row_mask:0xf bank_mask:0xa bound_ctrl:1
	v_pk_fma_f32 v[68:69], v[172:173], v[8:9], v[56:57] op_sel_hi:[0,1,1] neg_lo:[1,0,0] neg_hi:[1,0,0]
	v_pk_fma_f32 v[70:71], v[172:173], v[10:11], v[58:59] op_sel_hi:[0,1,1] neg_lo:[1,0,0] neg_hi:[1,0,0]
	s_waitcnt lgkmcnt(0)
	ds_read_b128 v[4:7], v156 offset:16896
	ds_read_b128 v[12:15], v156 offset:16928
	ds_read_u16_d16_hi v24, v157 offset:16896
	ds_read_b128 v[20:23], v156 offset:16960
	ds_read_b128 v[8:11], v156 offset:16912
	v_pk_mul_f32 v[174:175], v[68:69], v[28:29]
	v_pk_mul_f32 v[176:177], v[68:69], v[16:17]
	v_pk_fma_f32 v[174:175], v[70:71], v[30:31], v[174:175]
	v_pk_fma_f32 v[176:177], v[70:71], v[18:19], v[176:177]
	v_add_f32_e32 v174, v174, v175
	v_add_f32_e32 v190, v176, v177
	v_pk_mul_f32 v[52:53], v[48:49], v[36:37] op_sel_hi:[0,1]
	ds_read_b128 v[16:19], v156 offset:16944
	v_add_f32_dpp v174, v174, v174 row_ror:8 row_mask:0xf bank_mask:0xf bound_ctrl:1
	v_pk_mul_f32 v[54:55], v[48:49], v[38:39] op_sel_hi:[0,1]
	v_pk_fma_f32 v[56:57], v[68:69], v[44:45], v[52:53]
	v_add_f32_dpp v174, v174, v174 row_ror:4 row_mask:0xf bank_mask:0xf bound_ctrl:1
	v_pk_fma_f32 v[58:59], v[70:71], v[46:47], v[54:55]
	v_lshl_add_u64 v[150:151], v[150:151], 0, v[64:65]
	v_add_f32_dpp v174, v174, v174 row_ror:2 row_mask:0xf bank_mask:0xf bound_ctrl:1
	v_add_u32_e32 v158, s43, v162
	v_add_u32_e32 v159, s43, v163
	v_add_f32_dpp v174, v174, v174 row_ror:1 row_mask:0xf bank_mask:0xf bound_ctrl:1
	v_add_f32_dpp v241, v233, v233 row_half_mirror row_mask:0xf bank_mask:0xf bound_ctrl:1
	v_add_f32_dpp v241, v237, v237 row_half_mirror row_mask:0xf bank_mask:0xa bound_ctrl:1
	v_pk_fma_f32 v[68:69], v[174:175], v[32:33], v[56:57] op_sel_hi:[0,1,1] neg_lo:[1,0,0] neg_hi:[1,0,0]
	v_pk_fma_f32 v[70:71], v[174:175], v[34:35], v[58:59] op_sel_hi:[0,1,1] neg_lo:[1,0,0] neg_hi:[1,0,0]
	s_waitcnt lgkmcnt(0)
	ds_read_b128 v[28:31], v156 offset:18304
	ds_read_b128 v[36:39], v156 offset:18336
	ds_read_u16_d16_hi v48, v157 offset:18304
	ds_read_b128 v[44:47], v156 offset:18368
	ds_read_b128 v[32:35], v156 offset:18320
	v_pk_mul_f32 v[172:173], v[68:69], v[4:5]
	v_pk_mul_f32 v[178:179], v[68:69], v[40:41]
	v_pk_fma_f32 v[172:173], v[70:71], v[6:7], v[172:173]
	v_pk_fma_f32 v[178:179], v[70:71], v[42:43], v[178:179]
	v_add_f32_e32 v172, v172, v173
	v_add_f32_e32 v191, v178, v179
	v_pk_mul_f32 v[52:53], v[24:25], v[12:13] op_sel_hi:[0,1]
	ds_read_b128 v[40:43], v156 offset:18352
	v_add_f32_dpp v172, v172, v172 row_ror:8 row_mask:0xf bank_mask:0xf bound_ctrl:1
	v_pk_mul_f32 v[54:55], v[24:25], v[14:15] op_sel_hi:[0,1]
	v_pk_fma_f32 v[56:57], v[68:69], v[20:21], v[52:53]
	v_add_f32_dpp v172, v172, v172 row_ror:4 row_mask:0xf bank_mask:0xf bound_ctrl:1
	v_pk_fma_f32 v[58:59], v[70:71], v[22:23], v[54:55]
	v_add_f32_dpp v242, v238, v238 quad_perm:[3,2,1,0] row_mask:0xf bank_mask:0xf bound_ctrl:1
	v_add_f32_dpp v172, v172, v172 row_ror:2 row_mask:0xf bank_mask:0xf bound_ctrl:1
	v_add_f32_dpp v243, v240, v240 quad_perm:[3,2,1,0] row_mask:0xf bank_mask:0xf bound_ctrl:1
	v_cndmask_b32_e64 v244, v242, v243, s[4:5]
	v_add_f32_dpp v172, v172, v172 row_ror:1 row_mask:0xf bank_mask:0xf bound_ctrl:1
	v_pk_fma_f32 v[68:69], v[172:173], v[8:9], v[56:57] op_sel_hi:[0,1,1] neg_lo:[1,0,0] neg_hi:[1,0,0]
	v_pk_fma_f32 v[70:71], v[172:173], v[10:11], v[58:59] op_sel_hi:[0,1,1] neg_lo:[1,0,0] neg_hi:[1,0,0]
	s_waitcnt lgkmcnt(0)
	ds_read_b128 v[4:7], v156 offset:19712
	ds_read_b128 v[12:15], v156 offset:19744
	ds_read_u16_d16_hi v24, v157 offset:19712
	ds_read_b128 v[20:23], v156 offset:19776
	ds_read_b128 v[8:11], v156 offset:19728
	v_pk_mul_f32 v[174:175], v[68:69], v[28:29]
	v_pk_mul_f32 v[176:177], v[68:69], v[16:17]
	v_pk_fma_f32 v[174:175], v[70:71], v[30:31], v[174:175]
	v_pk_fma_f32 v[176:177], v[70:71], v[18:19], v[176:177]
	v_add_f32_e32 v174, v174, v175
	v_add_f32_e32 v192, v176, v177
	v_pk_mul_f32 v[52:53], v[48:49], v[36:37] op_sel_hi:[0,1]
	ds_read_b128 v[16:19], v156 offset:19760
	v_add_f32_dpp v174, v174, v174 row_ror:8 row_mask:0xf bank_mask:0xf bound_ctrl:1
	v_pk_mul_f32 v[54:55], v[48:49], v[38:39] op_sel_hi:[0,1]
	v_pk_fma_f32 v[56:57], v[68:69], v[44:45], v[52:53]
	v_add_f32_dpp v174, v174, v174 row_ror:4 row_mask:0xf bank_mask:0xf bound_ctrl:1
	v_pk_fma_f32 v[58:59], v[70:71], v[46:47], v[54:55]
	v_add_f32_dpp v242, v239, v239 quad_perm:[3,2,1,0] row_mask:0xf bank_mask:0xf bound_ctrl:1
	v_add_f32_dpp v174, v174, v174 row_ror:2 row_mask:0xf bank_mask:0xf bound_ctrl:1
	v_add_f32_dpp v243, v241, v241 quad_perm:[3,2,1,0] row_mask:0xf bank_mask:0xf bound_ctrl:1
	s_nop 0
	v_add_f32_dpp v174, v174, v174 row_ror:1 row_mask:0xf bank_mask:0xf bound_ctrl:1
	v_pk_fma_f32 v[68:69], v[174:175], v[32:33], v[56:57] op_sel_hi:[0,1,1] neg_lo:[1,0,0] neg_hi:[1,0,0]
	v_pk_fma_f32 v[70:71], v[174:175], v[34:35], v[58:59] op_sel_hi:[0,1,1] neg_lo:[1,0,0] neg_hi:[1,0,0]
	s_waitcnt lgkmcnt(0)
	ds_read_b128 v[28:31], v156 offset:21120
	ds_read_b128 v[36:39], v156 offset:21152
	ds_read_u16_d16_hi v48, v157 offset:21120
	ds_read_b128 v[44:47], v156 offset:21184
	ds_read_b128 v[32:35], v156 offset:21136
	v_pk_mul_f32 v[172:173], v[68:69], v[4:5]
	v_pk_mul_f32 v[178:179], v[68:69], v[40:41]
	v_pk_fma_f32 v[172:173], v[70:71], v[6:7], v[172:173]
	v_pk_fma_f32 v[178:179], v[70:71], v[42:43], v[178:179]
	v_add_f32_e32 v172, v172, v173
	v_add_f32_e32 v193, v178, v179
	v_pk_mul_f32 v[52:53], v[24:25], v[12:13] op_sel_hi:[0,1]
	ds_read_b128 v[40:43], v156 offset:21168
	v_add_f32_dpp v172, v172, v172 row_ror:8 row_mask:0xf bank_mask:0xf bound_ctrl:1
	v_pk_mul_f32 v[54:55], v[24:25], v[14:15] op_sel_hi:[0,1]
	v_pk_fma_f32 v[56:57], v[68:69], v[20:21], v[52:53]
	v_add_f32_dpp v172, v172, v172 row_ror:4 row_mask:0xf bank_mask:0xf bound_ctrl:1
	v_pk_fma_f32 v[58:59], v[70:71], v[22:23], v[54:55]
	v_cndmask_b32_e64 v245, v242, v243, s[4:5]
	v_add_f32_dpp v172, v172, v172 row_ror:2 row_mask:0xf bank_mask:0xf bound_ctrl:1
	v_add_f32_dpp v242, v244, v244 quad_perm:[1,0,3,2] row_mask:0xf bank_mask:0xf bound_ctrl:1
	s_nop 0
	v_add_f32_dpp v172, v172, v172 row_ror:1 row_mask:0xf bank_mask:0xf bound_ctrl:1
	v_pk_fma_f32 v[68:69], v[172:173], v[8:9], v[56:57] op_sel_hi:[0,1,1] neg_lo:[1,0,0] neg_hi:[1,0,0]
	v_pk_fma_f32 v[70:71], v[172:173], v[10:11], v[58:59] op_sel_hi:[0,1,1] neg_lo:[1,0,0] neg_hi:[1,0,0]
	s_waitcnt lgkmcnt(0)
; DEVI void rw_chain_task(const Params& p, int l, int seq, int head, int quarter, char* smem) {
;     ...
;     for (int c = 0; c < nch; c += 4) {
;       lds_barrier();
;       RW_STORE(R1, B1);
;       RW_LOAD(R1, c + 5);
;       RW_COMPUTE(B0, c);
;       lds_barrier();
;       RW_STORE(R2, B0);
;       RW_LOAD(R2, c + 6);
;       RW_COMPUTE(B1, c + 1);
;       lds_barrier();
;       RW_STORE(R3, B1);
;       RW_LOAD(R3, c + 7);
;       RW_COMPUTE(B0, c + 2);
;       lds_barrier();
;       RW_STORE(R0, B0);
;       RW_LOAD(R0, c + 8);
;       RW_COMPUTE(B1, c + 3);
;     }
	ds_read_b128 v[4:7], v158 offset:0
	ds_read_b128 v[12:15], v158 offset:32
	ds_read_u16_d16_hi v24, v159 offset:0
	ds_read_b128 v[20:23], v158 offset:64
	ds_read_b128 v[8:11], v158 offset:16
	v_pk_mul_f32 v[174:175], v[68:69], v[28:29]
	v_pk_mul_f32 v[176:177], v[68:69], v[16:17]
	v_pk_fma_f32 v[174:175], v[70:71], v[30:31], v[174:175]
	v_pk_fma_f32 v[176:177], v[70:71], v[18:19], v[176:177]
	v_add_f32_e32 v174, v174, v175
	v_add_f32_e32 v194, v176, v177
	v_pk_mul_f32 v[52:53], v[48:49], v[36:37] op_sel_hi:[0,1]
	ds_read_b128 v[16:19], v158 offset:48
	v_add_f32_dpp v174, v174, v174 row_ror:8 row_mask:0xf bank_mask:0xf bound_ctrl:1
	v_pk_mul_f32 v[54:55], v[48:49], v[38:39] op_sel_hi:[0,1]
	v_pk_fma_f32 v[56:57], v[68:69], v[44:45], v[52:53]
	v_add_f32_dpp v174, v174, v174 row_ror:4 row_mask:0xf bank_mask:0xf bound_ctrl:1
	v_pk_fma_f32 v[58:59], v[70:71], v[46:47], v[54:55]
	v_add_f32_dpp v243, v245, v245 quad_perm:[1,0,3,2] row_mask:0xf bank_mask:0xf bound_ctrl:1
	v_add_f32_dpp v174, v174, v174 row_ror:2 row_mask:0xf bank_mask:0xf bound_ctrl:1
	v_cndmask_b32_e64 v246, v242, v243, s[6:7]
	v_bfe_u32 v61, v246, 16, 1
	v_add3_u32 v61, v246, v61, s33
	global_store_short_d16_hi v[160:161], v61, off
	v_lshl_add_u64 v[160:161], v[160:161], 0, s[46:47]
	v_add_f32_dpp v174, v174, v174 row_ror:1 row_mask:0xf bank_mask:0xf bound_ctrl:1
	v_pk_fma_f32 v[68:69], v[174:175], v[32:33], v[56:57] op_sel_hi:[0,1,1] neg_lo:[1,0,0] neg_hi:[1,0,0]
	v_pk_fma_f32 v[70:71], v[174:175], v[34:35], v[58:59] op_sel_hi:[0,1,1] neg_lo:[1,0,0] neg_hi:[1,0,0]
	s_waitcnt lgkmcnt(0)
	s_barrier
	s_mov_b32 vcc_lo, s42
	s_mov_b32 s42, s43
	s_mov_b32 s43, s45
	s_mov_b32 s45, vcc_lo
	v_add_u32_e32 v156, s42, v162
	v_add_u32_e32 v157, s42, v163
	v_add_u32_e32 v155, s45, v164
	v_add_u32_e32 v165, s45, v167
	v_add_u32_e32 v166, s45, v168
	s_waitcnt lgkmcnt(0)
	ds_read_b128 v[28:31], v156 offset:1408
	ds_read_b128 v[36:39], v156 offset:1440
	ds_read_u16_d16_hi v48, v157 offset:1408
	ds_read_b128 v[44:47], v156 offset:1472
	ds_read_b128 v[32:35], v156 offset:1424
	v_pk_mul_f32 v[172:173], v[68:69], v[4:5]
	v_pk_mul_f32 v[178:179], v[68:69], v[40:41]
	v_pk_fma_f32 v[172:173], v[70:71], v[6:7], v[172:173]
	v_pk_fma_f32 v[178:179], v[70:71], v[42:43], v[178:179]
	v_add_f32_e32 v172, v172, v173
	v_add_f32_e32 v195, v178, v179
	v_pk_mul_f32 v[52:53], v[24:25], v[12:13] op_sel_hi:[0,1]
	ds_read_b128 v[40:43], v156 offset:1456
	v_add_f32_dpp v172, v172, v172 row_ror:8 row_mask:0xf bank_mask:0xf bound_ctrl:1
	v_pk_mul_f32 v[54:55], v[24:25], v[14:15] op_sel_hi:[0,1]
	v_pk_fma_f32 v[56:57], v[68:69], v[20:21], v[52:53]
	v_add_f32_dpp v172, v172, v172 row_ror:4 row_mask:0xf bank_mask:0xf bound_ctrl:1
	v_pk_fma_f32 v[58:59], v[70:71], v[22:23], v[54:55]
	s_nop 0
	v_add_f32_dpp v172, v172, v172 row_ror:2 row_mask:0xf bank_mask:0xf bound_ctrl:1
	s_nop 1
	v_add_f32_dpp v172, v172, v172 row_ror:1 row_mask:0xf bank_mask:0xf bound_ctrl:1
	v_pk_fma_f32 v[68:69], v[172:173], v[8:9], v[56:57] op_sel_hi:[0,1,1] neg_lo:[1,0,0] neg_hi:[1,0,0]
	v_pk_fma_f32 v[70:71], v[172:173], v[10:11], v[58:59] op_sel_hi:[0,1,1] neg_lo:[1,0,0] neg_hi:[1,0,0]
	s_waitcnt lgkmcnt(0)
	ds_read_b128 v[4:7], v156 offset:2816
	ds_read_b128 v[12:15], v156 offset:2848
	ds_read_u16_d16_hi v24, v157 offset:2816
	ds_read_b128 v[20:23], v156 offset:2880
	ds_read_b128 v[8:11], v156 offset:2832
	v_pk_mul_f32 v[174:175], v[68:69], v[28:29]
	v_pk_mul_f32 v[176:177], v[68:69], v[16:17]
	v_pk_fma_f32 v[174:175], v[70:71], v[30:31], v[174:175]
	v_pk_fma_f32 v[176:177], v[70:71], v[18:19], v[176:177]
	v_add_f32_e32 v174, v174, v175
	v_add_f32_e32 v196, v176, v177
	v_pk_mul_f32 v[52:53], v[48:49], v[36:37] op_sel_hi:[0,1]
	ds_read_b128 v[16:19], v156 offset:2864
	v_add_f32_dpp v174, v174, v174 row_ror:8 row_mask:0xf bank_mask:0xf bound_ctrl:1
	v_pk_mul_f32 v[54:55], v[48:49], v[38:39] op_sel_hi:[0,1]
	v_pk_fma_f32 v[56:57], v[68:69], v[44:45], v[52:53]
	v_add_f32_dpp v174, v174, v174 row_ror:4 row_mask:0xf bank_mask:0xf bound_ctrl:1
	v_pk_fma_f32 v[58:59], v[70:71], v[46:47], v[54:55]
	s_waitcnt vmcnt(12)
	v_add_f32_dpp v174, v174, v174 row_ror:2 row_mask:0xf bank_mask:0xf bound_ctrl:1
	v_lshlrev_b32_e32 v136, 16, v88
	v_and_b32_e32 v137, 0xffff0000, v88
	v_add_f32_dpp v174, v174, v174 row_ror:1 row_mask:0xf bank_mask:0xf bound_ctrl:1
	v_add_f32_dpp v230, v180, v180 row_mirror row_mask:0xf bank_mask:0xf bound_ctrl:1
	v_add_f32_dpp v230, v188, v188 row_mirror row_mask:0xf bank_mask:0xc bound_ctrl:1
	v_pk_fma_f32 v[68:69], v[174:175], v[32:33], v[56:57] op_sel_hi:[0,1,1] neg_lo:[1,0,0] neg_hi:[1,0,0]
	v_pk_fma_f32 v[70:71], v[174:175], v[34:35], v[58:59] op_sel_hi:[0,1,1] neg_lo:[1,0,0] neg_hi:[1,0,0]
	s_waitcnt lgkmcnt(0)
	ds_read_b128 v[28:31], v156 offset:4224
	ds_read_b128 v[36:39], v156 offset:4256
	ds_read_u16_d16_hi v48, v157 offset:4224
	ds_read_b128 v[44:47], v156 offset:4288
	ds_read_b128 v[32:35], v156 offset:4240
	v_pk_mul_f32 v[172:173], v[68:69], v[4:5]
	v_pk_mul_f32 v[178:179], v[68:69], v[40:41]
	v_pk_fma_f32 v[172:173], v[70:71], v[6:7], v[172:173]
	v_pk_fma_f32 v[178:179], v[70:71], v[42:43], v[178:179]
	v_add_f32_e32 v172, v172, v173
	v_add_f32_e32 v197, v178, v179
	v_pk_mul_f32 v[52:53], v[24:25], v[12:13] op_sel_hi:[0,1]
	ds_read_b128 v[40:43], v156 offset:4272
	v_add_f32_dpp v172, v172, v172 row_ror:8 row_mask:0xf bank_mask:0xf bound_ctrl:1
	v_pk_mul_f32 v[54:55], v[24:25], v[14:15] op_sel_hi:[0,1]
	v_pk_fma_f32 v[56:57], v[68:69], v[20:21], v[52:53]
	v_add_f32_dpp v172, v172, v172 row_ror:4 row_mask:0xf bank_mask:0xf bound_ctrl:1
	v_pk_fma_f32 v[58:59], v[70:71], v[22:23], v[54:55]
	v_lshlrev_b32_e32 v138, 16, v89
	v_add_f32_dpp v172, v172, v172 row_ror:2 row_mask:0xf bank_mask:0xf bound_ctrl:1
	v_and_b32_e32 v139, 0xffff0000, v89
	v_lshlrev_b32_e32 v140, 16, v90
	v_add_f32_dpp v172, v172, v172 row_ror:1 row_mask:0xf bank_mask:0xf bound_ctrl:1
	v_add_f32_dpp v231, v181, v181 row_mirror row_mask:0xf bank_mask:0xf bound_ctrl:1
	v_add_f32_dpp v231, v189, v189 row_mirror row_mask:0xf bank_mask:0xc bound_ctrl:1
	v_pk_fma_f32 v[68:69], v[172:173], v[8:9], v[56:57] op_sel_hi:[0,1,1] neg_lo:[1,0,0] neg_hi:[1,0,0]
	v_pk_fma_f32 v[70:71], v[172:173], v[10:11], v[58:59] op_sel_hi:[0,1,1] neg_lo:[1,0,0] neg_hi:[1,0,0]
	s_waitcnt lgkmcnt(0)
; DEVI void rw_chain_task(const Params& p, int l, int seq, int head, int quarter, char* smem) {
;     ...
;     for (int c = 0; c < nch; c += 4) {
;       lds_barrier();
;       RW_STORE(R1, B1);
;       RW_LOAD(R1, c + 5);
;       RW_COMPUTE(B0, c);
;       lds_barrier();
;       RW_STORE(R2, B0);
;       RW_LOAD(R2, c + 6);
;       RW_COMPUTE(B1, c + 1);
;       lds_barrier();
;       RW_STORE(R3, B1);
;       RW_LOAD(R3, c + 7);
;       RW_COMPUTE(B0, c + 2);
;       lds_barrier();
;       RW_STORE(R0, B0);
;       RW_LOAD(R0, c + 8);
;       RW_COMPUTE(B1, c + 3);
;     }
	ds_read_b128 v[4:7], v156 offset:5632
	ds_read_b128 v[12:15], v156 offset:5664
	ds_read_u16_d16_hi v24, v157 offset:5632
	ds_read_b128 v[20:23], v156 offset:5696
	ds_read_b128 v[8:11], v156 offset:5648
	v_pk_mul_f32 v[174:175], v[68:69], v[28:29]
	v_pk_mul_f32 v[176:177], v[68:69], v[16:17]
	v_pk_fma_f32 v[174:175], v[70:71], v[30:31], v[174:175]
	v_pk_fma_f32 v[176:177], v[70:71], v[18:19], v[176:177]
	v_add_f32_e32 v174, v174, v175
	v_add_f32_e32 v198, v176, v177
	v_pk_mul_f32 v[52:53], v[48:49], v[36:37] op_sel_hi:[0,1]
	ds_read_b128 v[16:19], v156 offset:5680
	v_add_f32_dpp v174, v174, v174 row_ror:8 row_mask:0xf bank_mask:0xf bound_ctrl:1
	v_pk_mul_f32 v[54:55], v[48:49], v[38:39] op_sel_hi:[0,1]
	v_pk_fma_f32 v[56:57], v[68:69], v[44:45], v[52:53]
	v_add_f32_dpp v174, v174, v174 row_ror:4 row_mask:0xf bank_mask:0xf bound_ctrl:1
	v_pk_fma_f32 v[58:59], v[70:71], v[46:47], v[54:55]
	v_and_b32_e32 v141, 0xffff0000, v90
	v_add_f32_dpp v174, v174, v174 row_ror:2 row_mask:0xf bank_mask:0xf bound_ctrl:1
	v_lshlrev_b32_e32 v142, 16, v91
	v_and_b32_e32 v143, 0xffff0000, v91
	v_add_f32_dpp v174, v174, v174 row_ror:1 row_mask:0xf bank_mask:0xf bound_ctrl:1
	v_add_f32_dpp v232, v182, v182 row_mirror row_mask:0xf bank_mask:0xf bound_ctrl:1
	v_add_f32_dpp v232, v190, v190 row_mirror row_mask:0xf bank_mask:0xc bound_ctrl:1
	v_pk_fma_f32 v[68:69], v[174:175], v[32:33], v[56:57] op_sel_hi:[0,1,1] neg_lo:[1,0,0] neg_hi:[1,0,0]
	v_pk_fma_f32 v[70:71], v[174:175], v[34:35], v[58:59] op_sel_hi:[0,1,1] neg_lo:[1,0,0] neg_hi:[1,0,0]
	s_waitcnt lgkmcnt(0)
	ds_read_b128 v[28:31], v156 offset:7040
	ds_read_b128 v[36:39], v156 offset:7072
	ds_read_u16_d16_hi v48, v157 offset:7040
	ds_read_b128 v[44:47], v156 offset:7104
	ds_read_b128 v[32:35], v156 offset:7056
	v_pk_mul_f32 v[172:173], v[68:69], v[4:5]
	v_pk_mul_f32 v[178:179], v[68:69], v[40:41]
	v_pk_fma_f32 v[172:173], v[70:71], v[6:7], v[172:173]
	v_pk_fma_f32 v[178:179], v[70:71], v[42:43], v[178:179]
	v_add_f32_e32 v172, v172, v173
	v_add_f32_e32 v199, v178, v179
	v_pk_mul_f32 v[52:53], v[24:25], v[12:13] op_sel_hi:[0,1]
	ds_read_b128 v[40:43], v156 offset:7088
	v_add_f32_dpp v172, v172, v172 row_ror:8 row_mask:0xf bank_mask:0xf bound_ctrl:1
	v_pk_mul_f32 v[54:55], v[24:25], v[14:15] op_sel_hi:[0,1]
	v_pk_fma_f32 v[56:57], v[68:69], v[20:21], v[52:53]
	v_add_f32_dpp v172, v172, v172 row_ror:4 row_mask:0xf bank_mask:0xf bound_ctrl:1
	v_pk_fma_f32 v[58:59], v[70:71], v[22:23], v[54:55]
	ds_write_b128 v155, v[136:139] offset:0
	v_add_f32_dpp v172, v172, v172 row_ror:2 row_mask:0xf bank_mask:0xf bound_ctrl:1
	ds_write_b128 v155, v[140:143] offset:80
	v_lshlrev_b32_e32 v136, 16, v92
	v_add_f32_dpp v172, v172, v172 row_ror:1 row_mask:0xf bank_mask:0xf bound_ctrl:1
	v_add_f32_dpp v233, v183, v183 row_mirror row_mask:0xf bank_mask:0xf bound_ctrl:1
	v_add_f32_dpp v233, v191, v191 row_mirror row_mask:0xf bank_mask:0xc bound_ctrl:1
	v_pk_fma_f32 v[68:69], v[172:173], v[8:9], v[56:57] op_sel_hi:[0,1,1] neg_lo:[1,0,0] neg_hi:[1,0,0]
	v_pk_fma_f32 v[70:71], v[172:173], v[10:11], v[58:59] op_sel_hi:[0,1,1] neg_lo:[1,0,0] neg_hi:[1,0,0]
	v_add_f32_dpp v234, v184, v184 row_mirror row_mask:0xf bank_mask:0xf bound_ctrl:1
	s_waitcnt lgkmcnt(2)
	ds_read_b128 v[4:7], v156 offset:8448
	ds_read_b128 v[12:15], v156 offset:8480
	ds_read_u16_d16_hi v24, v157 offset:8448
	ds_read_b128 v[20:23], v156 offset:8512
	ds_read_b128 v[8:11], v156 offset:8464
	v_pk_mul_f32 v[174:175], v[68:69], v[28:29]
	v_pk_mul_f32 v[176:177], v[68:69], v[16:17]
	v_pk_fma_f32 v[174:175], v[70:71], v[30:31], v[174:175]
	v_pk_fma_f32 v[176:177], v[70:71], v[18:19], v[176:177]
	v_add_f32_e32 v174, v174, v175
	v_add_f32_e32 v200, v176, v177
	v_pk_mul_f32 v[52:53], v[48:49], v[36:37] op_sel_hi:[0,1]
	ds_read_b128 v[16:19], v156 offset:8496
	v_add_f32_dpp v174, v174, v174 row_ror:8 row_mask:0xf bank_mask:0xf bound_ctrl:1
	v_pk_mul_f32 v[54:55], v[48:49], v[38:39] op_sel_hi:[0,1]
	v_pk_fma_f32 v[56:57], v[68:69], v[44:45], v[52:53]
	v_add_f32_dpp v174, v174, v174 row_ror:4 row_mask:0xf bank_mask:0xf bound_ctrl:1
	v_pk_fma_f32 v[58:59], v[70:71], v[46:47], v[54:55]
	v_and_b32_e32 v137, 0xffff0000, v92
	v_add_f32_dpp v174, v174, v174 row_ror:2 row_mask:0xf bank_mask:0xf bound_ctrl:1
	v_lshlrev_b32_e32 v138, 16, v93
	v_and_b32_e32 v139, 0xffff0000, v93
	v_add_f32_dpp v174, v174, v174 row_ror:1 row_mask:0xf bank_mask:0xf bound_ctrl:1
	v_add_f32_dpp v234, v192, v192 row_mirror row_mask:0xf bank_mask:0xc bound_ctrl:1
	v_add_f32_dpp v235, v185, v185 row_mirror row_mask:0xf bank_mask:0xf bound_ctrl:1
	v_pk_fma_f32 v[68:69], v[174:175], v[32:33], v[56:57] op_sel_hi:[0,1,1] neg_lo:[1,0,0] neg_hi:[1,0,0]
	v_pk_fma_f32 v[70:71], v[174:175], v[34:35], v[58:59] op_sel_hi:[0,1,1] neg_lo:[1,0,0] neg_hi:[1,0,0]
	s_waitcnt lgkmcnt(0)
	ds_read_b128 v[28:31], v156 offset:9856
	ds_read_b128 v[36:39], v156 offset:9888
	ds_read_u16_d16_hi v48, v157 offset:9856
	ds_read_b128 v[44:47], v156 offset:9920
	ds_read_b128 v[32:35], v156 offset:9872
	v_pk_mul_f32 v[172:173], v[68:69], v[4:5]
	v_pk_mul_f32 v[178:179], v[68:69], v[40:41]
	v_pk_fma_f32 v[172:173], v[70:71], v[6:7], v[172:173]
	v_pk_fma_f32 v[178:179], v[70:71], v[42:43], v[178:179]
	v_add_f32_e32 v172, v172, v173
	v_add_f32_e32 v201, v178, v179
	v_pk_mul_f32 v[52:53], v[24:25], v[12:13] op_sel_hi:[0,1]
	ds_read_b128 v[40:43], v156 offset:9904
	v_add_f32_dpp v172, v172, v172 row_ror:8 row_mask:0xf bank_mask:0xf bound_ctrl:1
	v_pk_mul_f32 v[54:55], v[24:25], v[14:15] op_sel_hi:[0,1]
	v_pk_fma_f32 v[56:57], v[68:69], v[20:21], v[52:53]
	v_add_f32_dpp v172, v172, v172 row_ror:4 row_mask:0xf bank_mask:0xf bound_ctrl:1
	v_pk_fma_f32 v[58:59], v[70:71], v[22:23], v[54:55]
	v_lshlrev_b32_e32 v140, 16, v94
	v_add_f32_dpp v172, v172, v172 row_ror:2 row_mask:0xf bank_mask:0xf bound_ctrl:1
	v_and_b32_e32 v141, 0xffff0000, v94
	v_lshlrev_b32_e32 v142, 16, v95
	v_add_f32_dpp v172, v172, v172 row_ror:1 row_mask:0xf bank_mask:0xf bound_ctrl:1
	v_add_f32_dpp v235, v193, v193 row_mirror row_mask:0xf bank_mask:0xc bound_ctrl:1
	v_add_f32_dpp v236, v186, v186 row_mirror row_mask:0xf bank_mask:0xf bound_ctrl:1
	v_pk_fma_f32 v[68:69], v[172:173], v[8:9], v[56:57] op_sel_hi:[0,1,1] neg_lo:[1,0,0] neg_hi:[1,0,0]
	v_pk_fma_f32 v[70:71], v[172:173], v[10:11], v[58:59] op_sel_hi:[0,1,1] neg_lo:[1,0,0] neg_hi:[1,0,0]
	s_waitcnt lgkmcnt(0)
; DEVI void rw_chain_task(const Params& p, int l, int seq, int head, int quarter, char* smem) {
;     ...
;     for (int c = 0; c < nch; c += 4) {
;       lds_barrier();
;       RW_STORE(R1, B1);
;       RW_LOAD(R1, c + 5);
;       RW_COMPUTE(B0, c);
;       lds_barrier();
;       RW_STORE(R2, B0);
;       RW_LOAD(R2, c + 6);
;       RW_COMPUTE(B1, c + 1);
;       lds_barrier();
;       RW_STORE(R3, B1);
;       RW_LOAD(R3, c + 7);
;       RW_COMPUTE(B0, c + 2);
;       lds_barrier();
;       RW_STORE(R0, B0);
;       RW_LOAD(R0, c + 8);
;       RW_COMPUTE(B1, c + 3);
;     }
	ds_read_b128 v[4:7], v156 offset:11264
	ds_read_b128 v[12:15], v156 offset:11296
	ds_read_u16_d16_hi v24, v157 offset:11264
	ds_read_b128 v[20:23], v156 offset:11328
	ds_read_b128 v[8:11], v156 offset:11280
	v_pk_mul_f32 v[174:175], v[68:69], v[28:29]
	v_pk_mul_f32 v[176:177], v[68:69], v[16:17]
	v_pk_fma_f32 v[174:175], v[70:71], v[30:31], v[174:175]
	v_pk_fma_f32 v[176:177], v[70:71], v[18:19], v[176:177]
	v_add_f32_e32 v174, v174, v175
	v_add_f32_e32 v210, v176, v177
	v_pk_mul_f32 v[52:53], v[48:49], v[36:37] op_sel_hi:[0,1]
	ds_read_b128 v[16:19], v156 offset:11312
	v_add_f32_dpp v174, v174, v174 row_ror:8 row_mask:0xf bank_mask:0xf bound_ctrl:1
	v_pk_mul_f32 v[54:55], v[48:49], v[38:39] op_sel_hi:[0,1]
	v_pk_fma_f32 v[56:57], v[68:69], v[44:45], v[52:53]
	v_add_f32_dpp v174, v174, v174 row_ror:4 row_mask:0xf bank_mask:0xf bound_ctrl:1
	v_pk_fma_f32 v[58:59], v[70:71], v[46:47], v[54:55]
	v_and_b32_e32 v143, 0xffff0000, v95
	v_add_f32_dpp v174, v174, v174 row_ror:2 row_mask:0xf bank_mask:0xf bound_ctrl:1
	ds_write_b128 v155, v[136:139] offset:11264
	ds_write_b128 v155, v[140:143] offset:11344
	v_add_f32_dpp v174, v174, v174 row_ror:1 row_mask:0xf bank_mask:0xf bound_ctrl:1
	v_add_f32_dpp v236, v194, v194 row_mirror row_mask:0xf bank_mask:0xc bound_ctrl:1
	v_add_f32_dpp v237, v187, v187 row_mirror row_mask:0xf bank_mask:0xf bound_ctrl:1
	v_pk_fma_f32 v[68:69], v[174:175], v[32:33], v[56:57] op_sel_hi:[0,1,1] neg_lo:[1,0,0] neg_hi:[1,0,0]
	v_pk_fma_f32 v[70:71], v[174:175], v[34:35], v[58:59] op_sel_hi:[0,1,1] neg_lo:[1,0,0] neg_hi:[1,0,0]
	s_waitcnt lgkmcnt(2)
	ds_read_b128 v[28:31], v156 offset:12672
	ds_read_b128 v[36:39], v156 offset:12704
	ds_read_u16_d16_hi v48, v157 offset:12672
	ds_read_b128 v[44:47], v156 offset:12736
	ds_read_b128 v[32:35], v156 offset:12688
	v_pk_mul_f32 v[172:173], v[68:69], v[4:5]
	v_pk_mul_f32 v[178:179], v[68:69], v[40:41]
	v_pk_fma_f32 v[172:173], v[70:71], v[6:7], v[172:173]
	v_pk_fma_f32 v[178:179], v[70:71], v[42:43], v[178:179]
	v_add_f32_e32 v172, v172, v173
	v_add_f32_e32 v211, v178, v179
	v_pk_mul_f32 v[52:53], v[24:25], v[12:13] op_sel_hi:[0,1]
	ds_read_b128 v[40:43], v156 offset:12720
	v_add_f32_dpp v172, v172, v172 row_ror:8 row_mask:0xf bank_mask:0xf bound_ctrl:1
	v_pk_mul_f32 v[54:55], v[24:25], v[14:15] op_sel_hi:[0,1]
	v_pk_fma_f32 v[56:57], v[68:69], v[20:21], v[52:53]
	v_add_f32_dpp v172, v172, v172 row_ror:4 row_mask:0xf bank_mask:0xf bound_ctrl:1
	v_pk_fma_f32 v[58:59], v[70:71], v[22:23], v[54:55]
	ds_write_b128 v165, v[96:99]
	v_add_f32_dpp v172, v172, v172 row_ror:2 row_mask:0xf bank_mask:0xf bound_ctrl:1
	ds_write_b128 v166, v[100:103]
	global_load_dwordx4 v[88:91], v[144:145], off
	v_add_f32_dpp v172, v172, v172 row_ror:1 row_mask:0xf bank_mask:0xf bound_ctrl:1
	v_add_f32_dpp v237, v195, v195 row_mirror row_mask:0xf bank_mask:0xc bound_ctrl:1
	v_add_f32_dpp v238, v230, v230 row_half_mirror row_mask:0xf bank_mask:0xf bound_ctrl:1
	v_pk_fma_f32 v[68:69], v[172:173], v[8:9], v[56:57] op_sel_hi:[0,1,1] neg_lo:[1,0,0] neg_hi:[1,0,0]
	v_pk_fma_f32 v[70:71], v[172:173], v[10:11], v[58:59] op_sel_hi:[0,1,1] neg_lo:[1,0,0] neg_hi:[1,0,0]
	v_add_f32_dpp v238, v234, v234 row_half_mirror row_mask:0xf bank_mask:0xa bound_ctrl:1
	s_waitcnt lgkmcnt(2)
	ds_read_b128 v[4:7], v156 offset:14080
	ds_read_b128 v[12:15], v156 offset:14112
	ds_read_u16_d16_hi v24, v157 offset:14080
	ds_read_b128 v[20:23], v156 offset:14144
	ds_read_b128 v[8:11], v156 offset:14096
	v_pk_mul_f32 v[174:175], v[68:69], v[28:29]
	v_pk_mul_f32 v[176:177], v[68:69], v[16:17]
	v_pk_fma_f32 v[174:175], v[70:71], v[30:31], v[174:175]
	v_pk_fma_f32 v[176:177], v[70:71], v[18:19], v[176:177]
	v_add_f32_e32 v174, v174, v175
	v_add_f32_e32 v212, v176, v177
	v_pk_mul_f32 v[52:53], v[48:49], v[36:37] op_sel_hi:[0,1]
	ds_read_b128 v[16:19], v156 offset:14128
	v_add_f32_dpp v174, v174, v174 row_ror:8 row_mask:0xf bank_mask:0xf bound_ctrl:1
	v_pk_mul_f32 v[54:55], v[48:49], v[38:39] op_sel_hi:[0,1]
	v_pk_fma_f32 v[56:57], v[68:69], v[44:45], v[52:53]
	v_add_f32_dpp v174, v174, v174 row_ror:4 row_mask:0xf bank_mask:0xf bound_ctrl:1
	v_pk_fma_f32 v[58:59], v[70:71], v[46:47], v[54:55]
	global_load_dwordx4 v[92:95], v[146:147], off
	v_add_f32_dpp v174, v174, v174 row_ror:2 row_mask:0xf bank_mask:0xf bound_ctrl:1
	global_load_dwordx4 v[96:99], v[148:149], off
	global_load_dwordx4 v[100:103], v[150:151], off
	v_add_f32_dpp v174, v174, v174 row_ror:1 row_mask:0xf bank_mask:0xf bound_ctrl:1
	v_add_f32_dpp v239, v231, v231 row_half_mirror row_mask:0xf bank_mask:0xf bound_ctrl:1
	v_add_f32_dpp v239, v235, v235 row_half_mirror row_mask:0xf bank_mask:0xa bound_ctrl:1
	v_pk_fma_f32 v[68:69], v[174:175], v[32:33], v[56:57] op_sel_hi:[0,1,1] neg_lo:[1,0,0] neg_hi:[1,0,0]
	v_pk_fma_f32 v[70:71], v[174:175], v[34:35], v[58:59] op_sel_hi:[0,1,1] neg_lo:[1,0,0] neg_hi:[1,0,0]
	s_waitcnt lgkmcnt(0)
; DEVI void rw_chain_task(const Params& p, int l, int seq, int head, int quarter, char* smem) {
;     ...
;     for (int c = 0; c < nch; c += 4) {
;       lds_barrier();
;       RW_STORE(R1, B1);
;       RW_LOAD(R1, c + 5);
;       RW_COMPUTE(B0, c);
;       lds_barrier();
;       RW_STORE(R2, B0);
;       RW_LOAD(R2, c + 6);
;       RW_COMPUTE(B1, c + 1);
;       lds_barrier();
;       RW_STORE(R3, B1);
;       RW_LOAD(R3, c + 7);
;       RW_COMPUTE(B0, c + 2);
;       lds_barrier();
;       RW_STORE(R0, B0);
;       RW_LOAD(R0, c + 8);
;       RW_COMPUTE(B1, c + 3);
;     }
	ds_read_b128 v[28:31], v156 offset:15488
	ds_read_b128 v[36:39], v156 offset:15520
	ds_read_u16_d16_hi v48, v157 offset:15488
	ds_read_b128 v[44:47], v156 offset:15552
	ds_read_b128 v[32:35], v156 offset:15504
	v_pk_mul_f32 v[172:173], v[68:69], v[4:5]
	v_pk_mul_f32 v[178:179], v[68:69], v[40:41]
	v_pk_fma_f32 v[172:173], v[70:71], v[6:7], v[172:173]
	v_pk_fma_f32 v[178:179], v[70:71], v[42:43], v[178:179]
	v_add_f32_e32 v172, v172, v173
	v_add_f32_e32 v213, v178, v179
	v_pk_mul_f32 v[52:53], v[24:25], v[12:13] op_sel_hi:[0,1]
	ds_read_b128 v[40:43], v156 offset:15536
	v_add_f32_dpp v172, v172, v172 row_ror:8 row_mask:0xf bank_mask:0xf bound_ctrl:1
	v_pk_mul_f32 v[54:55], v[24:25], v[14:15] op_sel_hi:[0,1]
	v_pk_fma_f32 v[56:57], v[68:69], v[20:21], v[52:53]
	v_add_f32_dpp v172, v172, v172 row_ror:4 row_mask:0xf bank_mask:0xf bound_ctrl:1
	v_pk_fma_f32 v[58:59], v[70:71], v[22:23], v[54:55]
	v_lshl_add_u64 v[144:145], v[144:145], 0, v[152:153]
	v_add_f32_dpp v172, v172, v172 row_ror:2 row_mask:0xf bank_mask:0xf bound_ctrl:1
	v_lshl_add_u64 v[146:147], v[146:147], 0, v[152:153]
	v_lshl_add_u64 v[148:149], v[148:149], 0, v[62:63]
	v_add_f32_dpp v172, v172, v172 row_ror:1 row_mask:0xf bank_mask:0xf bound_ctrl:1
	v_add_f32_dpp v240, v232, v232 row_half_mirror row_mask:0xf bank_mask:0xf bound_ctrl:1
	v_add_f32_dpp v240, v236, v236 row_half_mirror row_mask:0xf bank_mask:0xa bound_ctrl:1
	v_pk_fma_f32 v[68:69], v[172:173], v[8:9], v[56:57] op_sel_hi:[0,1,1] neg_lo:[1,0,0] neg_hi:[1,0,0]
	v_pk_fma_f32 v[70:71], v[172:173], v[10:11], v[58:59] op_sel_hi:[0,1,1] neg_lo:[1,0,0] neg_hi:[1,0,0]
	s_waitcnt lgkmcnt(0)
	ds_read_b128 v[4:7], v156 offset:16896
	ds_read_b128 v[12:15], v156 offset:16928
	ds_read_u16_d16_hi v24, v157 offset:16896
	ds_read_b128 v[20:23], v156 offset:16960
	ds_read_b128 v[8:11], v156 offset:16912
	v_pk_mul_f32 v[174:175], v[68:69], v[28:29]
	v_pk_mul_f32 v[176:177], v[68:69], v[16:17]
	v_pk_fma_f32 v[174:175], v[70:71], v[30:31], v[174:175]
	v_pk_fma_f32 v[176:177], v[70:71], v[18:19], v[176:177]
	v_add_f32_e32 v174, v174, v175
	v_add_f32_e32 v220, v176, v177
	v_pk_mul_f32 v[52:53], v[48:49], v[36:37] op_sel_hi:[0,1]
	ds_read_b128 v[16:19], v156 offset:16944
	v_add_f32_dpp v174, v174, v174 row_ror:8 row_mask:0xf bank_mask:0xf bound_ctrl:1
	v_pk_mul_f32 v[54:55], v[48:49], v[38:39] op_sel_hi:[0,1]
	v_pk_fma_f32 v[56:57], v[68:69], v[44:45], v[52:53]
	v_add_f32_dpp v174, v174, v174 row_ror:4 row_mask:0xf bank_mask:0xf bound_ctrl:1
	v_pk_fma_f32 v[58:59], v[70:71], v[46:47], v[54:55]
	v_lshl_add_u64 v[150:151], v[150:151], 0, v[64:65]
	v_add_f32_dpp v174, v174, v174 row_ror:2 row_mask:0xf bank_mask:0xf bound_ctrl:1
	v_add_u32_e32 v158, s43, v162
	v_add_u32_e32 v159, s43, v163
	v_add_f32_dpp v174, v174, v174 row_ror:1 row_mask:0xf bank_mask:0xf bound_ctrl:1
	v_add_f32_dpp v241, v233, v233 row_half_mirror row_mask:0xf bank_mask:0xf bound_ctrl:1
	v_add_f32_dpp v241, v237, v237 row_half_mirror row_mask:0xf bank_mask:0xa bound_ctrl:1
	v_pk_fma_f32 v[68:69], v[174:175], v[32:33], v[56:57] op_sel_hi:[0,1,1] neg_lo:[1,0,0] neg_hi:[1,0,0]
	v_pk_fma_f32 v[70:71], v[174:175], v[34:35], v[58:59] op_sel_hi:[0,1,1] neg_lo:[1,0,0] neg_hi:[1,0,0]
	s_waitcnt lgkmcnt(0)
	ds_read_b128 v[28:31], v156 offset:18304
	ds_read_b128 v[36:39], v156 offset:18336
	ds_read_u16_d16_hi v48, v157 offset:18304
	ds_read_b128 v[44:47], v156 offset:18368
	ds_read_b128 v[32:35], v156 offset:18320
	v_pk_mul_f32 v[172:173], v[68:69], v[4:5]
	v_pk_mul_f32 v[178:179], v[68:69], v[40:41]
	v_pk_fma_f32 v[172:173], v[70:71], v[6:7], v[172:173]
	v_pk_fma_f32 v[178:179], v[70:71], v[42:43], v[178:179]
	v_add_f32_e32 v172, v172, v173
	v_add_f32_e32 v221, v178, v179
	v_pk_mul_f32 v[52:53], v[24:25], v[12:13] op_sel_hi:[0,1]
	ds_read_b128 v[40:43], v156 offset:18352
	v_add_f32_dpp v172, v172, v172 row_ror:8 row_mask:0xf bank_mask:0xf bound_ctrl:1
	v_pk_mul_f32 v[54:55], v[24:25], v[14:15] op_sel_hi:[0,1]
	v_pk_fma_f32 v[56:57], v[68:69], v[20:21], v[52:53]
	v_add_f32_dpp v172, v172, v172 row_ror:4 row_mask:0xf bank_mask:0xf bound_ctrl:1
	v_pk_fma_f32 v[58:59], v[70:71], v[22:23], v[54:55]
	v_add_f32_dpp v242, v238, v238 quad_perm:[3,2,1,0] row_mask:0xf bank_mask:0xf bound_ctrl:1
	v_add_f32_dpp v172, v172, v172 row_ror:2 row_mask:0xf bank_mask:0xf bound_ctrl:1
	v_add_f32_dpp v243, v240, v240 quad_perm:[3,2,1,0] row_mask:0xf bank_mask:0xf bound_ctrl:1
	v_cndmask_b32_e64 v244, v242, v243, s[4:5]
	v_add_f32_dpp v172, v172, v172 row_ror:1 row_mask:0xf bank_mask:0xf bound_ctrl:1
	v_pk_fma_f32 v[68:69], v[172:173], v[8:9], v[56:57] op_sel_hi:[0,1,1] neg_lo:[1,0,0] neg_hi:[1,0,0]
	v_pk_fma_f32 v[70:71], v[172:173], v[10:11], v[58:59] op_sel_hi:[0,1,1] neg_lo:[1,0,0] neg_hi:[1,0,0]
	s_waitcnt lgkmcnt(0)
	ds_read_b128 v[4:7], v156 offset:19712
	ds_read_b128 v[12:15], v156 offset:19744
	ds_read_u16_d16_hi v24, v157 offset:19712
	ds_read_b128 v[20:23], v156 offset:19776
	ds_read_b128 v[8:11], v156 offset:19728
	v_pk_mul_f32 v[174:175], v[68:69], v[28:29]
	v_pk_mul_f32 v[176:177], v[68:69], v[16:17]
	v_pk_fma_f32 v[174:175], v[70:71], v[30:31], v[174:175]
	v_pk_fma_f32 v[176:177], v[70:71], v[18:19], v[176:177]
	v_add_f32_e32 v174, v174, v175
	v_add_f32_e32 v222, v176, v177
	v_pk_mul_f32 v[52:53], v[48:49], v[36:37] op_sel_hi:[0,1]
	ds_read_b128 v[16:19], v156 offset:19760
	v_add_f32_dpp v174, v174, v174 row_ror:8 row_mask:0xf bank_mask:0xf bound_ctrl:1
	v_pk_mul_f32 v[54:55], v[48:49], v[38:39] op_sel_hi:[0,1]
	v_pk_fma_f32 v[56:57], v[68:69], v[44:45], v[52:53]
	v_add_f32_dpp v174, v174, v174 row_ror:4 row_mask:0xf bank_mask:0xf bound_ctrl:1
	v_pk_fma_f32 v[58:59], v[70:71], v[46:47], v[54:55]
	v_add_f32_dpp v242, v239, v239 quad_perm:[3,2,1,0] row_mask:0xf bank_mask:0xf bound_ctrl:1
	v_add_f32_dpp v174, v174, v174 row_ror:2 row_mask:0xf bank_mask:0xf bound_ctrl:1
	v_add_f32_dpp v243, v241, v241 quad_perm:[3,2,1,0] row_mask:0xf bank_mask:0xf bound_ctrl:1
	s_nop 0
	v_add_f32_dpp v174, v174, v174 row_ror:1 row_mask:0xf bank_mask:0xf bound_ctrl:1
	v_pk_fma_f32 v[68:69], v[174:175], v[32:33], v[56:57] op_sel_hi:[0,1,1] neg_lo:[1,0,0] neg_hi:[1,0,0]
	v_pk_fma_f32 v[70:71], v[174:175], v[34:35], v[58:59] op_sel_hi:[0,1,1] neg_lo:[1,0,0] neg_hi:[1,0,0]
	s_waitcnt lgkmcnt(0)
; DEVI void rw_chain_task(const Params& p, int l, int seq, int head, int quarter, char* smem) {
;     ...
;       RW_COMPUTE(B1, c + 1);
;       lds_barrier();
;       RW_STORE(R3, B1);
;       RW_LOAD(R3, c + 7);
;       RW_COMPUTE(B0, c + 2);
;       lds_barrier();
;       RW_STORE(R0, B0);
;       RW_LOAD(R0, c + 8);
;       RW_COMPUTE(B1, c + 3);
;     }
	ds_read_b128 v[28:31], v156 offset:21120
	ds_read_b128 v[36:39], v156 offset:21152
	ds_read_u16_d16_hi v48, v157 offset:21120
	ds_read_b128 v[44:47], v156 offset:21184
	ds_read_b128 v[32:35], v156 offset:21136
	v_pk_mul_f32 v[172:173], v[68:69], v[4:5]
	v_pk_mul_f32 v[178:179], v[68:69], v[40:41]
	v_pk_fma_f32 v[172:173], v[70:71], v[6:7], v[172:173]
	v_pk_fma_f32 v[178:179], v[70:71], v[42:43], v[178:179]
	v_add_f32_e32 v172, v172, v173
	v_add_f32_e32 v223, v178, v179
	v_pk_mul_f32 v[52:53], v[24:25], v[12:13] op_sel_hi:[0,1]
	ds_read_b128 v[40:43], v156 offset:21168
	v_add_f32_dpp v172, v172, v172 row_ror:8 row_mask:0xf bank_mask:0xf bound_ctrl:1
	v_pk_mul_f32 v[54:55], v[24:25], v[14:15] op_sel_hi:[0,1]
	v_pk_fma_f32 v[56:57], v[68:69], v[20:21], v[52:53]
	v_add_f32_dpp v172, v172, v172 row_ror:4 row_mask:0xf bank_mask:0xf bound_ctrl:1
	v_pk_fma_f32 v[58:59], v[70:71], v[22:23], v[54:55]
	v_cndmask_b32_e64 v245, v242, v243, s[4:5]
	v_add_f32_dpp v172, v172, v172 row_ror:2 row_mask:0xf bank_mask:0xf bound_ctrl:1
	v_add_f32_dpp v242, v244, v244 quad_perm:[1,0,3,2] row_mask:0xf bank_mask:0xf bound_ctrl:1
	s_nop 0
	v_add_f32_dpp v172, v172, v172 row_ror:1 row_mask:0xf bank_mask:0xf bound_ctrl:1
	v_pk_fma_f32 v[68:69], v[172:173], v[8:9], v[56:57] op_sel_hi:[0,1,1] neg_lo:[1,0,0] neg_hi:[1,0,0]
	v_pk_fma_f32 v[70:71], v[172:173], v[10:11], v[58:59] op_sel_hi:[0,1,1] neg_lo:[1,0,0] neg_hi:[1,0,0]
	s_waitcnt lgkmcnt(0)
	ds_read_b128 v[4:7], v158 offset:0
	ds_read_b128 v[12:15], v158 offset:32
	ds_read_u16_d16_hi v24, v159 offset:0
	ds_read_b128 v[20:23], v158 offset:64
	ds_read_b128 v[8:11], v158 offset:16
	v_pk_mul_f32 v[174:175], v[68:69], v[28:29]
	v_pk_mul_f32 v[176:177], v[68:69], v[16:17]
	v_pk_fma_f32 v[174:175], v[70:71], v[30:31], v[174:175]
	v_pk_fma_f32 v[176:177], v[70:71], v[18:19], v[176:177]
	v_add_f32_e32 v174, v174, v175
	v_add_f32_e32 v224, v176, v177
	v_pk_mul_f32 v[52:53], v[48:49], v[36:37] op_sel_hi:[0,1]
	ds_read_b128 v[16:19], v158 offset:48
	v_add_f32_dpp v174, v174, v174 row_ror:8 row_mask:0xf bank_mask:0xf bound_ctrl:1
	v_pk_mul_f32 v[54:55], v[48:49], v[38:39] op_sel_hi:[0,1]
	v_pk_fma_f32 v[56:57], v[68:69], v[44:45], v[52:53]
	v_add_f32_dpp v174, v174, v174 row_ror:4 row_mask:0xf bank_mask:0xf bound_ctrl:1
	v_pk_fma_f32 v[58:59], v[70:71], v[46:47], v[54:55]
	v_add_f32_dpp v243, v245, v245 quad_perm:[1,0,3,2] row_mask:0xf bank_mask:0xf bound_ctrl:1
	v_add_f32_dpp v174, v174, v174 row_ror:2 row_mask:0xf bank_mask:0xf bound_ctrl:1
	v_cndmask_b32_e64 v246, v242, v243, s[6:7]
	v_bfe_u32 v61, v246, 16, 1
	v_add3_u32 v61, v246, v61, s33
	global_store_short_d16_hi v[160:161], v61, off
	v_lshl_add_u64 v[160:161], v[160:161], 0, s[46:47]
	v_add_f32_dpp v174, v174, v174 row_ror:1 row_mask:0xf bank_mask:0xf bound_ctrl:1
	v_pk_fma_f32 v[68:69], v[174:175], v[32:33], v[56:57] op_sel_hi:[0,1,1] neg_lo:[1,0,0] neg_hi:[1,0,0]
	v_pk_fma_f32 v[70:71], v[174:175], v[34:35], v[58:59] op_sel_hi:[0,1,1] neg_lo:[1,0,0] neg_hi:[1,0,0]
	s_add_u32 s41, s41, 4
	s_cmpk_lt_u32 s41, 0x400
	s_cbranch_scc1 .Lrwc_loop
; DEVI void rw_chain_task(const Params& p, int l, int seq, int head, int quarter, char* smem) {
;     ...
;   float* so = seq < 2 ? p.out + O_PRWS + ((((size_t)l * 2 + seq) * 12 + head) * 64 + i) * 64 + jl * 4
;                       : p.out + O_SRWS + ((((size_t)l * 8 + (seq - 2)) * 12 + head) * 64 + i) * 64 + jl * 4;
;   *(float4*)so = make_float4(S[0], S[1], S[2], S[3]);
	s_waitcnt lgkmcnt(0)
	v_pk_mul_f32 v[178:179], v[68:69], v[40:41]
	v_pk_fma_f32 v[178:179], v[70:71], v[42:43], v[178:179]
	v_add_f32_e32 v225, v178, v179
	v_add_f32_dpp v230, v196, v196 row_mirror row_mask:0xf bank_mask:0xf bound_ctrl:1
	v_add_f32_dpp v230, v212, v212 row_mirror row_mask:0xf bank_mask:0xc bound_ctrl:1
	v_add_f32_dpp v231, v197, v197 row_mirror row_mask:0xf bank_mask:0xf bound_ctrl:1
	v_add_f32_dpp v231, v213, v213 row_mirror row_mask:0xf bank_mask:0xc bound_ctrl:1
	v_add_f32_dpp v232, v198, v198 row_mirror row_mask:0xf bank_mask:0xf bound_ctrl:1
	v_add_f32_dpp v232, v220, v220 row_mirror row_mask:0xf bank_mask:0xc bound_ctrl:1
	v_add_f32_dpp v233, v199, v199 row_mirror row_mask:0xf bank_mask:0xf bound_ctrl:1
	v_add_f32_dpp v233, v221, v221 row_mirror row_mask:0xf bank_mask:0xc bound_ctrl:1
	v_add_f32_dpp v234, v200, v200 row_mirror row_mask:0xf bank_mask:0xf bound_ctrl:1
	v_add_f32_dpp v234, v222, v222 row_mirror row_mask:0xf bank_mask:0xc bound_ctrl:1
	v_add_f32_dpp v235, v201, v201 row_mirror row_mask:0xf bank_mask:0xf bound_ctrl:1
	v_add_f32_dpp v235, v223, v223 row_mirror row_mask:0xf bank_mask:0xc bound_ctrl:1
	v_add_f32_dpp v236, v210, v210 row_mirror row_mask:0xf bank_mask:0xf bound_ctrl:1
	v_add_f32_dpp v236, v224, v224 row_mirror row_mask:0xf bank_mask:0xc bound_ctrl:1
	v_add_f32_dpp v237, v211, v211 row_mirror row_mask:0xf bank_mask:0xf bound_ctrl:1
	v_add_f32_dpp v237, v225, v225 row_mirror row_mask:0xf bank_mask:0xc bound_ctrl:1
	v_add_f32_dpp v238, v230, v230 row_half_mirror row_mask:0xf bank_mask:0xf bound_ctrl:1
	v_add_f32_dpp v238, v234, v234 row_half_mirror row_mask:0xf bank_mask:0xa bound_ctrl:1
	v_add_f32_dpp v239, v231, v231 row_half_mirror row_mask:0xf bank_mask:0xf bound_ctrl:1
	v_add_f32_dpp v239, v235, v235 row_half_mirror row_mask:0xf bank_mask:0xa bound_ctrl:1
	v_add_f32_dpp v240, v232, v232 row_half_mirror row_mask:0xf bank_mask:0xf bound_ctrl:1
	v_add_f32_dpp v240, v236, v236 row_half_mirror row_mask:0xf bank_mask:0xa bound_ctrl:1
	v_add_f32_dpp v241, v233, v233 row_half_mirror row_mask:0xf bank_mask:0xf bound_ctrl:1
	v_add_f32_dpp v241, v237, v237 row_half_mirror row_mask:0xf bank_mask:0xa bound_ctrl:1
	v_add_f32_dpp v242, v238, v238 quad_perm:[3,2,1,0] row_mask:0xf bank_mask:0xf bound_ctrl:1
	v_add_f32_dpp v243, v240, v240 quad_perm:[3,2,1,0] row_mask:0xf bank_mask:0xf bound_ctrl:1
	v_cndmask_b32_e64 v244, v242, v243, s[4:5]
	v_add_f32_dpp v242, v239, v239 quad_perm:[3,2,1,0] row_mask:0xf bank_mask:0xf bound_ctrl:1
	v_add_f32_dpp v243, v241, v241 quad_perm:[3,2,1,0] row_mask:0xf bank_mask:0xf bound_ctrl:1
	v_cndmask_b32_e64 v245, v242, v243, s[4:5]
	v_add_f32_dpp v242, v244, v244 quad_perm:[1,0,3,2] row_mask:0xf bank_mask:0xf bound_ctrl:1
	s_nop 0
	v_add_f32_dpp v243, v245, v245 quad_perm:[1,0,3,2] row_mask:0xf bank_mask:0xf bound_ctrl:1
	v_cndmask_b32_e64 v246, v242, v243, s[6:7]
	v_bfe_u32 v61, v246, 16, 1
	v_add3_u32 v61, v246, v61, s33
	global_store_short_d16_hi v[160:161], v61, off
	s_waitcnt vmcnt(0)
	v_cmp_eq_u32_e64 s[4:5], 0, v3
	v_cmp_eq_u32_e64 s[6:7], 1, v3
	v_cmp_eq_u32_e64 s[8:9], 2, v3
	v_cmp_eq_u32_e64 s[10:11], 3, v3
	v_cmp_eq_u32_e64 s[12:13], 4, v3
	v_cmp_eq_u32_e64 s[14:15], 5, v3
	v_cmp_eq_u32_e64 s[16:17], 6, v3
	v_cmp_eq_u32_e64 s[18:19], 7, v3
	v_cmp_eq_u32_e64 s[20:21], 8, v3
	v_cmp_eq_u32_e64 s[22:23], 9, v3
	v_cmp_eq_u32_e64 s[24:25], 10, v3
	v_cmp_eq_u32_e64 s[26:27], 11, v3
	v_cmp_eq_u32_e64 s[28:29], 12, v3
	v_cmp_eq_u32_e64 s[30:31], 13, v3
	v_cmp_eq_u32_e64 s[34:35], 14, v3
	v_cmp_eq_u32_e64 s[36:37], 15, v3
	s_movk_i32 s41, 0x3fc
	s_mov_b32 s42, 0xffff0000
	s_mov_b32 s43, 0xfffd0000
	s_mov_b32 s45, 0xfffe0000
	s_mov_b64 s[46:47], 0x40000
	v_readlane_b32 s38, v253, 39
	v_readlane_b32 s39, v253, 40
	v_and_b32_e32 v136, 16, v1
	v_cmp_eq_u32_e32 vcc, 0, v136
	v_readlane_b32 s4, v254, 2
	s_lshl_b32 s4, s4, 1
	v_readlane_b32 s6, v253, 37
	v_readlane_b32 s5, v254, 3
	v_readlane_b32 s7, v253, 38
	s_add_u32 s4, s4, s6
	s_addc_u32 s5, 0, s7
	s_mul_i32 s5, s5, 12
	s_mul_hi_u32 s6, s4, 12
	s_add_i32 s6, s6, s5
	s_mul_i32 s4, s4, 12
	v_readlane_b32 s5, v253, 4
	s_add_u32 s4, s4, s5
	v_readlane_b32 s5, v253, 5
	s_addc_u32 s5, s6, s5
	s_lshl_b64 s[4:5], s[4:5], 14
	v_readlane_b32 s6, v253, 2
	v_ashrrev_i32_e32 v155, 31, v154
	s_add_u32 s4, s6, s4
	v_readlane_b32 s6, v253, 3
	s_addc_u32 s5, s6, s5
	s_waitcnt vmcnt(19)
	v_lshlrev_b64 v[4:5], 8, v[154:155]
	v_lshl_add_u64 v[4:5], s[4:5], 0, v[4:5]
	v_lshlrev_b32_e32 v6, 4, v3
	v_mov_b32_e32 v7, v2
	v_lshl_add_u64 v[4:5], v[4:5], 0, v[6:7]
	s_barrier
	global_store_dwordx4 v[4:5], v[68:71], off
	s_and_b64 vcc, exec, s[2:3]
	s_cbranch_vccnz .LBB0_1001
